# v12: V tile staged with natural key-row order (DMA source offsets un-swapped) so P is used as produced - no permlane32_swap in the loop
# speedup vs baseline: 1.0627x; 1.0048x over previous
; __device__ __forceinline__ int v_rd_base(int lane) { return ((lane & 3) << 3) | (((lane >> 2) & 3) << 6) | (((lane >> 4) & 1) << 5) | (((lane >> 5) & 1) << 8); }
; #define RAWBAR() do { asm volatile("s_waitcnt lgkmcnt(0)" ::: "memory"); __builtin_amdgcn_s_barrier(); asm volatile("" ::: "memory"); } while (0)
; #define RAWBAR() do { asm volatile("s_waitcnt lgkmcnt(0)" ::: "memory"); __builtin_amdgcn_s_barrier(); asm volatile("" ::: "memory"); } while (0)
; #define RAWBAR() do { asm volatile("s_waitcnt lgkmcnt(0)" ::: "memory"); __builtin_amdgcn_s_barrier(); asm volatile("" ::: "memory"); } while (0)
; #define RAWBAR() do { asm volatile("s_waitcnt lgkmcnt(0)" ::: "memory"); __builtin_amdgcn_s_barrier(); asm volatile("" ::: "memory"); } while (0)
; #define RAWBAR() do { asm volatile("s_waitcnt lgkmcnt(0)" ::: "memory"); __builtin_amdgcn_s_barrier(); asm volatile("" ::: "memory"); } while (0)
; #define RAWBAR() do { asm volatile("s_waitcnt lgkmcnt(0)" ::: "memory"); __builtin_amdgcn_s_barrier(); asm volatile("" ::: "memory"); } while (0)
; template <int MODE> ...
;     ...
;   const bf16* Qw = Qb + (long)(g * 32 + r32) * 128 + hi * 8;
; #pragma unroll
;   for (int d0 = 0; d0 < 8; ++d0) qr[d0] = St::ld8(Qw + d0 * 16);
;   const int vb0 = (int)(uintptr_t)V_lds + v_rd_base(lane) + 2 * kh * 4096;
;   const int krow = 32 * kh + r32;
;   typedef __attribute__((address_space(3))) unsigned lds_u32;
;   const int wu = __builtin_amdgcn_readfirstlane(wid);
;   long gk[2], gv[2];
; #pragma unroll
;   for (int c = 0; c < 2; ++c) { const int q = wu + 8 * c;
;     const int r = 4 * q + (lane >> 4), pch = lane & 15; gk[c] = (long)r * 128 + ((pch ^ (r & 7)) * 8);
;     const int st = 2 * q + (lane >> 5), kk = (st >> 2) * 8 + ((lane >> 2) & 7), k = (kk & ~0xC) | ((kk & 4) << 1) | ((kk & 8) >> 1), cc = (st & 3) * 32 + (lane & 3) * 8;
;     gv[c] = (long)k * 256 + cc; }
;     ...
;   const int NT = seq / KVBLK;
;   STAGE(0, 0); asm volatile("s_waitcnt vmcnt(0)" ::: "memory"); RAWBAR();
.LBB0_1017:
	s_mov_b64 s[24:25], -1
	s_and_b64 vcc, exec, s[22:23]
	s_cbranch_vccz .LBB0_1010
	s_ashr_i32 s29, s28, 31
	s_mul_i32 s2, s40, 0x8200
	s_lshl_b64 s[22:23], s[28:29], 7
	v_mov_b32_e32 v197, v224
	s_mul_hi_i32 s3, s40, 0x8200
	s_add_u32 s2, s2, s22
	s_addc_u32 s3, s3, s23
	v_ashrrev_i32_e32 v213, 7, v197
	v_and_b32_e32 v206, 31, v197
	v_lshlrev_b32_e32 v196, 5, v213
	s_lshl_b64 s[2:3], s[2:3], 8
	v_or_b32_e32 v0, v196, v206
	s_add_u32 s34, s52, s2
	v_ashrrev_i32_e32 v1, 31, v0
	s_addc_u32 s35, s53, s3
	s_mul_i32 s26, s40, 0x820000
	v_bfe_u32 v207, v197, 5, 1
	v_lshlrev_b64 v[0:1], 8, v[0:1]
	s_mul_hi_i32 s27, s40, 0x820000
	s_add_u32 s36, s47, s26
	v_lshl_add_u64 v[0:1], s[34:35], 0, v[0:1]
	v_lshlrev_b32_e32 v194, 4, v207
	s_addc_u32 s37, s48, s27
	v_lshl_add_u64 v[0:1], v[0:1], 0, v[194:195]
	v_ashrrev_i32_e32 v8, 6, v197
	s_add_u32 s30, s49, s26
	global_load_dwordx4 v[188:191], v[0:1], off
	global_load_dwordx4 v[184:187], v[0:1], off offset:32
	global_load_dwordx4 v[180:183], v[0:1], off offset:64
	global_load_dwordx4 v[176:179], v[0:1], off offset:96
	global_load_dwordx4 v[172:175], v[0:1], off offset:128
	global_load_dwordx4 v[168:171], v[0:1], off offset:160
	global_load_dwordx4 v[164:167], v[0:1], off offset:192
	global_load_dwordx4 v[160:163], v[0:1], off offset:224
	v_readfirstlane_b32 s2, v8
	v_bfe_u32 v0, v197, 2, 2
	v_lshrrev_b32_e32 v1, 1, v197
	s_addc_u32 s31, s50, s27
	v_bfe_u32 v4, v197, 4, 2
	v_and_or_b32 v7, v1, 8, v0
	v_lshlrev_b32_e32 v0, 3, v197
	s_lshl_b32 s3, s2, 2
	s_lshl_b32 s24, s2, 1
	v_and_b32_e32 v13, 24, v0
	v_or_b32_e32 v0, s3, v4
	s_and_b32 s3, s3, -16
	s_and_b32 s25, s24, 4
	v_and_b32_e32 v2, 63, v197
	s_or_b32 s3, s3, s25
	v_lshlrev_b32_e32 v9, 3, v2
	v_lshlrev_b32_e32 v212, 4, v2
	v_or_b32_e32 v2, s3, v7
	s_add_i32 s3, s2, 8
	v_and_or_b32 v14, s24, 2, v207
	s_lshl_b32 s24, s3, 2
	s_lshl_b32 s25, s3, 1
	v_or_b32_e32 v4, s24, v4
	s_and_b32 s24, s24, -16
	s_and_b32 s33, s25, 4
	v_and_b32_e32 v6, 15, v197
	v_ashrrev_i32_e32 v1, 31, v0
	s_or_b32 s24, s24, s33
	v_and_b32_e32 v12, 0x100, v9
	v_bitop3_b32 v11, v0, v6, 7 bitop3:0x6c
	v_ashrrev_i32_e32 v5, 31, v4
	v_bitop3_b32 v15, v4, v6, 7 bitop3:0x6c
	v_or_b32_e32 v6, s24, v7
	v_and_b32_e32 v211, 1, v8
	v_and_b32_e32 v17, 24, v9
	v_lshlrev_b64 v[8:9], 8, v[0:1]
	s_lshl_b32 s24, s2, 10
	v_lshlrev_b32_e32 v10, 1, v197
	v_and_or_b32 v16, s25, 2, v207
	v_lshl_or_b32 v8, v11, 4, v8
	s_add_i32 s25, s24, 0
	v_lshlrev_b64 v[4:5], 8, v[4:5]
	v_lshlrev_b32_e32 v15, 4, v15
	v_ashrrev_i32_e32 v3, 31, v2
	v_and_b32_e32 v19, 32, v10
	v_lshl_add_u64 v[10:11], s[36:37], 0, v[8:9]
	s_mov_b32 m0, s25
	v_or_b32_e32 v4, v4, v15
	v_ashrrev_i32_e32 v7, 31, v6
	global_load_lds_dwordx4 v[10:11], off
	v_lshl_add_u64 v[128:129], v[10:11], 0, s[18:19]
	v_lshl_add_u64 v[4:5], s[36:37], 0, v[4:5]
	v_lshl_add_u64 v[130:131], v[4:5], 0, s[18:19]
	s_add_i32 m0, s25, 0x2000
	v_lshlrev_b32_e32 v1, 6, v14
	v_lshlrev_b32_e32 v10, 1, v13
	v_lshlrev_b64 v[2:3], 9, v[2:3]
	global_load_lds_dwordx4 v[4:5], off
	s_add_i32 m0, s25, 0x4000
	s_nop 0
	global_load_lds_dwordx4 v[128:129], off
	s_add_i32 m0, s25, 0x6000
	s_nop 0
	global_load_lds_dwordx4 v[130:131], off
	v_or3_b32 v4, v1, v10, v2
	v_lshrrev_b32_e32 v132, 11, v4
	v_lshrrev_b32_e32 v133, 12, v4
	v_xor_b32_e32 v132, v132, v133
	v_and_b32_e32 v132, 1, v132
	v_mul_u32_u24_e32 v132, 0x1800, v132
	v_xor_b32_e32 v4, v4, v132
	v_mov_b32_e32 v5, v3
	v_lshlrev_b32_e32 v1, 6, v16
	v_lshlrev_b64 v[6:7], 9, v[6:7]
	v_lshl_add_u64 v[4:5], s[30:31], 0, v[4:5]
	s_add_i32 m0, s25, 0x8000
	v_or3_b32 v10, v1, v10, v6
	v_lshrrev_b32_e32 v132, 11, v10
	v_lshrrev_b32_e32 v133, 12, v10
	v_xor_b32_e32 v132, v132, v133
	v_and_b32_e32 v132, 1, v132
	v_mul_u32_u24_e32 v132, 0x1800, v132
	v_xor_b32_e32 v10, v10, v132
	v_mov_b32_e32 v11, v7
	global_load_lds_dwordx4 v[4:5], off
	v_lshl_add_u64 v[10:11], s[30:31], 0, v[10:11]
	s_add_i32 m0, s25, 0xa000
	v_lshl_add_u64 v[4:5], v[4:5], 0, s[10:11]
	global_load_lds_dwordx4 v[10:11], off
	s_add_i32 m0, s25, 0xc000
	s_add_i32 s33, 0, 0x8000
	global_load_lds_dwordx4 v[4:5], off
	v_lshl_add_u64 v[4:5], v[10:11], 0, s[10:11]
	s_add_i32 m0, s25, 0xe000
	v_lshlrev_b32_e32 v20, 13, v211
	global_load_lds_dwordx4 v[4:5], off
	s_cmp_lg_u32 s33, -1
	v_lshl_or_b32 v1, v206, 8, v20
	s_cselect_b32 s41, s33, 0
	s_and_b32 s2, s2, 1
	v_lshlrev_b32_e32 v4, 4, v197
	v_add_u32_e32 v216, 0, v1
	s_lshl_b32 s2, s2, 6
	v_and_b32_e32 v1, 32, v197
	v_and_b32_e32 v5, 0x70, v4
	v_bitop3_b32 v225, v194, v4, s58 bitop3:0x78
	v_or3_b32 v4, s2, v1, v13
	s_and_b32 s2, s3, 1
	s_lshl_b32 s2, s2, 6
	v_or3_b32 v1, s2, v1, v13
	v_add_u32_e32 v0, 32, v0
	v_and_b32_e32 v18, 0xc0, v212
	s_waitcnt vmcnt(0)
	v_lshl_or_b32 v6, v1, 1, v6
	v_ashrrev_i32_e32 v1, 31, v0
	s_waitcnt lgkmcnt(0)
	s_barrier
; __device__ __forceinline__ int v_rd_base(int lane) { return ((lane & 3) << 3) | (((lane >> 2) & 3) << 6) | (((lane >> 4) & 1) << 5) | (((lane >> 5) & 1) << 8); }
; #define RAWBAR() do { asm volatile("s_waitcnt lgkmcnt(0)" ::: "memory"); __builtin_amdgcn_s_barrier(); asm volatile("" ::: "memory"); } while (0)
; #define RAWBAR() do { asm volatile("s_waitcnt lgkmcnt(0)" ::: "memory"); __builtin_amdgcn_s_barrier(); asm volatile("" ::: "memory"); } while (0)
; #define RAWBAR() do { asm volatile("s_waitcnt lgkmcnt(0)" ::: "memory"); __builtin_amdgcn_s_barrier(); asm volatile("" ::: "memory"); } while (0)
; template <int MODE> ...
;     ...
;   f32x16 o[8] = {}; bf16x8 qr[8]; float lsum = 0.f;
;   const bf16* Qw = Qb + (long)(g * 32 + r32) * 128 + hi * 8;
; #pragma unroll
;   for (int d0 = 0; d0 < 8; ++d0) qr[d0] = St::ld8(Qw + d0 * 16);
;   const int vb0 = (int)(uintptr_t)V_lds + v_rd_base(lane) + 2 * kh * 4096;
;   const int krow = 32 * kh + r32;
;   typedef __attribute__((address_space(3))) unsigned lds_u32;
;   const int wu = __builtin_amdgcn_readfirstlane(wid);
;   long gk[2], gv[2];
; #pragma unroll
;   for (int c = 0; c < 2; ++c) { const int q = wu + 8 * c;
;     const int r = 4 * q + (lane >> 4), pch = lane & 15; gk[c] = (long)r * 128 + ((pch ^ (r & 7)) * 8);
;     const int st = 2 * q + (lane >> 5), kk = (st >> 2) * 8 + ((lane >> 2) & 7), k = (kk & ~0xC) | ((kk & 4) << 1) | ((kk & 8) >> 1), cc = (st & 3) * 32 + (lane & 3) * 8;
;     gv[c] = (long)k * 256 + cc; }
;     ...
;   const int NT = seq / KVBLK;
;   STAGE(0, 0); asm volatile("s_waitcnt vmcnt(0)" ::: "memory"); RAWBAR();
;   if (false) __builtin_amdgcn_s_setprio(1);
;   for (int j = 0; j < NT; ++j) {
;     const int buf = j & 1;
;     if (j + 1 < NT) { STAGE((j + 1) * KVBLK, buf ^ 1); }
;     const char* Kb = K_lds + buf * 16384;
;     f32x16 pe = {}, po = {};
; #pragma unroll
;     for (int d0 = 0; d0 < 8; d0 += 2) {
;       const bf16x8 k0 = *reinterpret_cast<const bf16x8*>(Kb + KSWZ(krow, (d0 * 16 + hi * 8) * 2));
;       const bf16x8 k1 = *reinterpret_cast<const bf16x8*>(Kb + KSWZ(krow, ((d0 + 1) * 16 + hi * 8) * 2));
;       pe = __builtin_amdgcn_mfma_f32_32x32x16_bf16(k0, qr[d0], pe, 0, 0, 0);
;       po = __builtin_amdgcn_mfma_f32_32x32x16_bf16(k1, qr[d0 + 1], po, 0, 0, 0); }
	v_add_u32_e32 v10, s41, v18
	v_readlane_b32 s84, v251, 28
	v_lshlrev_b64 v[0:1], 8, v[0:1]
	v_add3_u32 v10, v10, v17, v19
	v_lshl_or_b32 v2, v4, 1, v2
	v_readlane_b32 s85, v251, 29
	v_or_b32_e32 v0, v0, v15
	v_mov_b32_e32 v215, 0
	s_mov_b32 s25, 0
	v_add3_u32 v214, v10, v12, v20
	v_bitop3_b32 v223, v194, v5, 32 bitop3:0x36
	v_bitop3_b32 v222, v194, v5, 64 bitop3:0x36
	v_bitop3_b32 v221, v194, v5, s43 bitop3:0x36
	v_bitop3_b32 v220, v194, v5, s59 bitop3:0x36
	v_bitop3_b32 v219, v194, v5, s60 bitop3:0x36
	v_bitop3_b32 v218, v194, v5, s56 bitop3:0x36
	v_bitop3_b32 v217, v194, v5, s61 bitop3:0x36
	v_lshl_add_u64 v[198:199], s[84:85], 0, v[2:3]
	v_lshl_add_u64 v[200:201], s[84:85], 0, v[6:7]
	v_lshl_add_u64 v[202:203], s[6:7], 0, v[8:9]
	v_lshl_add_u64 v[204:205], s[6:7], 0, v[0:1]
	v_mov_b32_e32 v0, 0
	v_mov_b32_e32 v1, v215
	v_mov_b32_e32 v2, v215
	v_mov_b32_e32 v3, v215
	v_mov_b32_e32 v4, v215
	v_mov_b32_e32 v5, v215
	v_mov_b32_e32 v6, v215
	v_mov_b32_e32 v7, v215
	v_mov_b32_e32 v8, v215
	v_mov_b32_e32 v9, v215
	v_mov_b32_e32 v10, v215
	v_mov_b32_e32 v11, v215
	v_mov_b32_e32 v12, v215
	v_mov_b32_e32 v13, v215
	v_mov_b32_e32 v14, v215
	v_mov_b32_e32 v15, v215
	v_mov_b32_e32 v16, 0
	v_mov_b32_e32 v17, v215
	v_mov_b32_e32 v18, v215
	v_mov_b32_e32 v19, v215
	v_mov_b32_e32 v20, v215
	v_mov_b32_e32 v21, v215
	v_mov_b32_e32 v22, v215
	v_mov_b32_e32 v23, v215
	v_mov_b32_e32 v24, v215
	v_mov_b32_e32 v25, v215
	v_mov_b32_e32 v26, v215
	v_mov_b32_e32 v27, v215
	v_mov_b32_e32 v28, v215
	v_mov_b32_e32 v29, v215
	v_mov_b32_e32 v30, v215
	v_mov_b32_e32 v31, v215
	v_mov_b32_e32 v32, 0
	v_mov_b32_e32 v33, v215
	v_mov_b32_e32 v34, v215
	v_mov_b32_e32 v35, v215
	v_mov_b32_e32 v36, v215
	v_mov_b32_e32 v37, v215
	v_mov_b32_e32 v38, v215
	v_mov_b32_e32 v39, v215
	v_mov_b32_e32 v40, v215
	v_mov_b32_e32 v41, v215
	v_mov_b32_e32 v42, v215
	v_mov_b32_e32 v43, v215
	v_mov_b32_e32 v44, v215
	v_mov_b32_e32 v45, v215
	v_mov_b32_e32 v46, v215
	v_mov_b32_e32 v47, v215
	v_mov_b32_e32 v48, 0
	v_mov_b32_e32 v49, v215
	v_mov_b32_e32 v50, v215
	v_mov_b32_e32 v51, v215
	v_mov_b32_e32 v52, v215
	v_mov_b32_e32 v53, v215
	v_mov_b32_e32 v54, v215
	v_mov_b32_e32 v55, v215
	v_mov_b32_e32 v56, v215
	v_mov_b32_e32 v57, v215
	v_mov_b32_e32 v58, v215
	v_mov_b32_e32 v59, v215
	v_mov_b32_e32 v60, v215
	v_mov_b32_e32 v61, v215
	v_mov_b32_e32 v62, v215
	v_mov_b32_e32 v63, v215
	v_mov_b32_e32 v64, 0
	v_mov_b32_e32 v65, v215
	v_mov_b32_e32 v66, v215
	v_mov_b32_e32 v67, v215
	v_mov_b32_e32 v68, v215
	v_mov_b32_e32 v69, v215
	v_mov_b32_e32 v70, v215
	v_mov_b32_e32 v71, v215
	v_mov_b32_e32 v72, v215
	v_mov_b32_e32 v73, v215
	v_mov_b32_e32 v74, v215
	v_mov_b32_e32 v75, v215
	v_mov_b32_e32 v76, v215
	v_mov_b32_e32 v77, v215
	v_mov_b32_e32 v78, v215
	v_mov_b32_e32 v79, v215
	v_mov_b32_e32 v80, 0
	v_mov_b32_e32 v81, v215
	v_mov_b32_e32 v82, v215
	v_mov_b32_e32 v83, v215
	v_mov_b32_e32 v84, v215
	v_mov_b32_e32 v85, v215
	v_mov_b32_e32 v86, v215
	v_mov_b32_e32 v87, v215
	v_mov_b32_e32 v88, v215
	v_mov_b32_e32 v89, v215
	v_mov_b32_e32 v90, v215
	v_mov_b32_e32 v91, v215
	v_mov_b32_e32 v92, v215
	v_mov_b32_e32 v93, v215
	v_mov_b32_e32 v94, v215
	v_mov_b32_e32 v95, v215
	v_mov_b32_e32 v96, 0
	v_mov_b32_e32 v97, v215
	v_mov_b32_e32 v98, v215
	v_mov_b32_e32 v99, v215
	v_mov_b32_e32 v100, v215
	v_mov_b32_e32 v101, v215
	v_mov_b32_e32 v102, v215
	v_mov_b32_e32 v103, v215
	v_mov_b32_e32 v104, v215
	v_mov_b32_e32 v105, v215
	v_mov_b32_e32 v106, v215
	v_mov_b32_e32 v107, v215
	v_mov_b32_e32 v108, v215
	v_mov_b32_e32 v109, v215
	v_mov_b32_e32 v110, v215
	v_mov_b32_e32 v111, v215
	v_mov_b32_e32 v112, 0
	v_mov_b32_e32 v113, v215
	v_mov_b32_e32 v114, v215
	v_mov_b32_e32 v115, v215
	v_mov_b32_e32 v116, v215
	v_mov_b32_e32 v117, v215
	v_mov_b32_e32 v118, v215
	v_mov_b32_e32 v119, v215
	v_mov_b32_e32 v120, v215
	v_mov_b32_e32 v121, v215
	v_mov_b32_e32 v122, v215
	v_mov_b32_e32 v123, v215
	v_mov_b32_e32 v124, v215
	v_mov_b32_e32 v125, v215
	v_mov_b32_e32 v126, v215
	v_mov_b32_e32 v127, v215
	v_readlane_b32 s86, v251, 30
	v_readlane_b32 s87, v251, 31
	s_waitcnt vmcnt(0)
	v_subrev_u32_e32 v220, s6, v202
	v_subrev_u32_e32 v219, s6, v204
	v_subrev_u32_e32 v218, s84, v198
	v_subrev_u32_e32 v217, s84, v200
	v_lshrrev_b32_e32 v242, 11, v218
	v_lshrrev_b32_e32 v243, 12, v218
	v_xor_b32_e32 v242, v242, v243
	v_and_b32_e32 v242, 1, v242
	v_mul_u32_u24_e32 v242, 0x1800, v242
	v_xor_b32_e32 v218, v218, v242
	v_lshrrev_b32_e32 v242, 11, v217
	v_lshrrev_b32_e32 v243, 12, v217
	v_xor_b32_e32 v242, v242, v243
	v_and_b32_e32 v242, 1, v242
	v_mul_u32_u24_e32 v242, 0x1800, v242
	v_xor_b32_e32 v217, v217, v242
	v_add_u32_e32 v242, 0x100, v218
	v_add_u32_e32 v243, 0x100, v217
	s_add_u32 s86, s6, s26
	s_addc_u32 s87, s7, s27
	s_add_u32 s86, s86, 0x4000
	s_addc_u32 s87, s87, 0
	s_add_u32 s2, s84, s26
	s_addc_u32 s3, s85, s27
	s_add_u32 s2, s2, s12
	s_addc_u32 s3, s3, s13
	v_add_u32_e32 v225, v216, v225
	v_add_u32_e32 v223, v216, v223
	v_add_u32_e32 v222, v216, v222
	v_add_u32_e32 v221, v216, v221
	ds_read_b128 v[226:229], v225 offset:0
	ds_read_b128 v[230:233], v223 offset:0
	s_waitcnt lgkmcnt(0)
	v_mfma_f32_32x32x16_bf16 v[144:159], v[226:229], v[188:191], 0
	v_mfma_f32_32x32x16_bf16 v[144:159], v[230:233], v[184:187], v[144:159]
	ds_read_b128 v[226:229], v222 offset:0
	ds_read_b128 v[230:233], v221 offset:0
	s_waitcnt lgkmcnt(0)
	v_mfma_f32_32x32x16_bf16 v[144:159], v[226:229], v[180:183], v[144:159]
	v_mfma_f32_32x32x16_bf16 v[144:159], v[230:233], v[176:179], v[144:159]
	ds_read_b128 v[226:229], v225 offset:128
	ds_read_b128 v[230:233], v223 offset:128
	s_waitcnt lgkmcnt(0)
	v_mfma_f32_32x32x16_bf16 v[144:159], v[226:229], v[172:175], v[144:159]
	v_mfma_f32_32x32x16_bf16 v[144:159], v[230:233], v[168:171], v[144:159]
	ds_read_b128 v[226:229], v222 offset:128
	ds_read_b128 v[230:233], v221 offset:128
	s_waitcnt lgkmcnt(0)
	v_mfma_f32_32x32x16_bf16 v[144:159], v[226:229], v[164:167], v[144:159]
	v_mfma_f32_32x32x16_bf16 v[144:159], v[230:233], v[160:163], v[144:159]
	s_mov_b32 s84, 0
	s_barrier
	s_cmp_lt_u32 s24, 0x1000
	s_cbranch_scc0 .LattnBpre_m0
; #define SBAR() __builtin_amdgcn_sched_barrier(0)
; #define PVR(S, DA, DB, vbase) do { S[0] = tr_read<v_rd_off(DA, 0, 0)>(vbase); S[1] = tr_read<v_rd_off(DA, 0, 1)>(vbase); S[2] = tr_read<v_rd_off(DB, 0, 0)>(vbase); S[3] = tr_read<v_rd_off(DB, 0, 1)>(vbase); \
;     S[4] = tr_read<v_rd_off(DA, 1, 0)>(vbase); S[5] = tr_read<v_rd_off(DA, 1, 1)>(vbase); S[6] = tr_read<v_rd_off(DB, 1, 0)>(vbase); S[7] = tr_read<v_rd_off(DB, 1, 1)>(vbase); } while (0)
; #define RAWBAR() do { asm volatile("s_waitcnt lgkmcnt(0)" ::: "memory"); __builtin_amdgcn_s_barrier(); asm volatile("" ::: "memory"); } while (0)
; #define RAWBAR() do { asm volatile("s_waitcnt lgkmcnt(0)" ::: "memory"); __builtin_amdgcn_s_barrier(); asm volatile("" ::: "memory"); } while (0)
; #define RAWBAR() do { asm volatile("s_waitcnt lgkmcnt(0)" ::: "memory"); __builtin_amdgcn_s_barrier(); asm volatile("" ::: "memory"); } while (0)
; #define RAWBAR() do { asm volatile("s_waitcnt lgkmcnt(0)" ::: "memory"); __builtin_amdgcn_s_barrier(); asm volatile("" ::: "memory"); } while (0)
; #define RAWBAR() do { asm volatile("s_waitcnt lgkmcnt(0)" ::: "memory"); __builtin_amdgcn_s_barrier(); asm volatile("" ::: "memory"); } while (0)
; template <int MODE> ...
;     ...
;   for (int j = 0; j < NT; ++j) {
;     const int buf = j & 1;
;     if (j + 1 < NT) { STAGE((j + 1) * KVBLK, buf ^ 1); }
;     const char* Kb = K_lds + buf * 16384;
;     f32x16 pe = {}, po = {};
; #pragma unroll
;     for (int d0 = 0; d0 < 8; d0 += 2) {
;       const bf16x8 k0 = *reinterpret_cast<const bf16x8*>(Kb + KSWZ(krow, (d0 * 16 + hi * 8) * 2));
;       const bf16x8 k1 = *reinterpret_cast<const bf16x8*>(Kb + KSWZ(krow, ((d0 + 1) * 16 + hi * 8) * 2));
;       pe = __builtin_amdgcn_mfma_f32_32x32x16_bf16(k0, qr[d0], pe, 0, 0, 0);
;       po = __builtin_amdgcn_mfma_f32_32x32x16_bf16(k1, qr[d0 + 1], po, 0, 0, 0); }
;     const int vo = vb0 + buf * 32768;
;     s16x4 R0_[8], R1_[8];
;     PVR(R0_, 0, 1, vo);
;     f32x16 p;
; #pragma unroll
;     for (int r = 0; r < 16; ++r) p[r] = __builtin_amdgcn_exp2f(fmaf(pe[r] + po[r], C, negMc));
;     float ps = 0.f;
; #pragma unroll
;     for (int r = 0; r < 16; ++r) ps += p[r];
;     lsum += ps;
;     const bf16x8 own0 = pk8(p, 0), own1 = pk8(p, 8);
;     SBAR();
;     PV_TAIL4(o, vo, vo + 16384, own0, own1);
;     asm volatile("s_waitcnt vmcnt(0)" ::: "memory");
;     RAWBAR();
.LBB0_1019:
	ds_read_b128 v[226:229], v225 offset:16384
	ds_read_b128 v[230:233], v223 offset:16384
	ds_read_b128 v[234:237], v222 offset:16384
	ds_read_b128 v[238:241], v221 offset:16384
	s_mov_b32 m0, s24
	s_nop 0
	global_load_lds_dwordx4 v220, s[86:87]
	s_add_i32 m0, s24, 0x2000
	s_nop 0
	global_load_lds_dwordx4 v219, s[86:87]
	v_exp_f32_e32 v144, v144
	v_exp_f32_e32 v145, v145
	v_exp_f32_e32 v146, v146
	v_exp_f32_e32 v147, v147
	s_waitcnt lgkmcnt(2)
	v_mfma_f32_32x32x16_bf16 v[128:143], v[226:229], v[188:191], 0
	v_mfma_f32_32x32x16_bf16 v[128:143], v[230:233], v[184:187], v[128:143]
	ds_read_b128 v[226:229], v225 offset:16512
	ds_read_b128 v[230:233], v223 offset:16512
	v_exp_f32_e32 v148, v148
	v_exp_f32_e32 v149, v149
	v_exp_f32_e32 v150, v150
	v_exp_f32_e32 v151, v151
	v_add_f32_e32 v246, v144, v145
	v_add_f32_e32 v246, v146, v246
	v_add_f32_e32 v246, v147, v246
	s_waitcnt lgkmcnt(2)
	v_mfma_f32_32x32x16_bf16 v[128:143], v[234:237], v[180:183], v[128:143]
	v_mfma_f32_32x32x16_bf16 v[128:143], v[238:241], v[176:179], v[128:143]
	ds_read_b128 v[234:237], v222 offset:16512
	ds_read_b128 v[238:241], v221 offset:16512
	v_exp_f32_e32 v152, v152
	v_exp_f32_e32 v153, v153
	v_exp_f32_e32 v154, v154
	v_exp_f32_e32 v155, v155
	v_add_f32_e32 v246, v148, v246
	v_add_f32_e32 v246, v149, v246
	v_add_f32_e32 v246, v150, v246
	v_add_f32_e32 v246, v151, v246
	s_waitcnt lgkmcnt(2)
	v_mfma_f32_32x32x16_bf16 v[128:143], v[226:229], v[172:175], v[128:143]
	v_mfma_f32_32x32x16_bf16 v[128:143], v[230:233], v[168:171], v[128:143]
	v_exp_f32_e32 v156, v156
	v_exp_f32_e32 v157, v157
	v_exp_f32_e32 v158, v158
	v_exp_f32_e32 v159, v159
	v_add_f32_e32 v246, v152, v246
	v_add_f32_e32 v246, v153, v246
	v_add_f32_e32 v246, v154, v246
	v_add_f32_e32 v246, v155, v246
	v_cvt_pk_bf16_f32 v226, v144, v145
	v_cvt_pk_bf16_f32 v227, v146, v147
	v_cvt_pk_bf16_f32 v228, v148, v149
	v_cvt_pk_bf16_f32 v229, v150, v151
	s_waitcnt lgkmcnt(0)
	v_mfma_f32_32x32x16_bf16 v[128:143], v[234:237], v[164:167], v[128:143]
	v_mfma_f32_32x32x16_bf16 v[128:143], v[238:241], v[160:163], v[128:143]
	v_add_u32_e32 v245, s84, v214
	s_add_i32 s85, s84, 0x8000
	s_cmp_eq_u32 s85, 0x18000
	s_cselect_b32 s85, 0, s85
	ds_read_b64_tr_b16 v[234:235], v245 offset:0
	ds_read_b64_tr_b16 v[236:237], v245 offset:2048
	ds_read_b64_tr_b16 v[238:239], v245 offset:512
	ds_read_b64_tr_b16 v[240:241], v245 offset:2560
	ds_read_b64_tr_b16 v[144:145], v245 offset:4096
	ds_read_b64_tr_b16 v[146:147], v245 offset:6144
	ds_read_b64_tr_b16 v[148:149], v245 offset:4608
	ds_read_b64_tr_b16 v[150:151], v245 offset:6656
	v_add_f32_e32 v246, v156, v246
	v_add_f32_e32 v246, v157, v246
	v_add_f32_e32 v246, v158, v246
	v_add_f32_e32 v246, v159, v246
	v_cvt_pk_bf16_f32 v230, v152, v153
	v_cvt_pk_bf16_f32 v231, v154, v155
	v_cvt_pk_bf16_f32 v232, v156, v157
	v_cvt_pk_bf16_f32 v233, v158, v159
	v_add_f32_e32 v215, v215, v246
	ds_read_b64_tr_b16 v[152:153], v245 offset:1024
	ds_read_b64_tr_b16 v[154:155], v245 offset:3072
	ds_read_b64_tr_b16 v[156:157], v245 offset:1536
	ds_read_b64_tr_b16 v[158:159], v245 offset:3584
	s_waitcnt lgkmcnt(8)
	v_mfma_f32_32x32x16_bf16 v[112:127], v[226:229], v[234:237], v[112:127]
	v_mfma_f32_32x32x16_bf16 v[96:111], v[226:229], v[238:241], v[96:111]
	ds_read_b64_tr_b16 v[234:235], v245 offset:5120
	ds_read_b64_tr_b16 v[236:237], v245 offset:7168
	ds_read_b64_tr_b16 v[238:239], v245 offset:5632
	ds_read_b64_tr_b16 v[240:241], v245 offset:7680
	s_add_i32 s41, s85, s24
	s_add_i32 m0, s41, 0x8000
	s_nop 0
	global_load_lds_dwordx4 v218, s[2:3]
	s_waitcnt lgkmcnt(8)
	v_mfma_f32_32x32x16_bf16 v[112:127], v[230:233], v[144:147], v[112:127]
	v_mfma_f32_32x32x16_bf16 v[96:111], v[230:233], v[148:151], v[96:111]
	ds_read_b64_tr_b16 v[144:145], v245 offset:16384
	ds_read_b64_tr_b16 v[146:147], v245 offset:18432
	ds_read_b64_tr_b16 v[148:149], v245 offset:16896
	ds_read_b64_tr_b16 v[150:151], v245 offset:18944
	s_add_i32 s41, s85, s24
	s_add_i32 m0, s41, 0xa000
	s_nop 0
	global_load_lds_dwordx4 v217, s[2:3]
	s_waitcnt lgkmcnt(8)
	v_mfma_f32_32x32x16_bf16 v[80:95], v[226:229], v[152:155], v[80:95]
	v_mfma_f32_32x32x16_bf16 v[64:79], v[226:229], v[156:159], v[64:79]
	ds_read_b64_tr_b16 v[152:153], v245 offset:20480
	ds_read_b64_tr_b16 v[154:155], v245 offset:22528
	ds_read_b64_tr_b16 v[156:157], v245 offset:20992
	ds_read_b64_tr_b16 v[158:159], v245 offset:23040
	s_add_i32 s41, s85, s24
	s_add_i32 m0, s41, 0xc000
	s_nop 0
	global_load_lds_dwordx4 v242, s[2:3]
	s_waitcnt lgkmcnt(8)
	v_mfma_f32_32x32x16_bf16 v[80:95], v[230:233], v[234:237], v[80:95]
	v_mfma_f32_32x32x16_bf16 v[64:79], v[230:233], v[238:241], v[64:79]
	ds_read_b64_tr_b16 v[234:235], v245 offset:17408
	ds_read_b64_tr_b16 v[236:237], v245 offset:19456
	ds_read_b64_tr_b16 v[238:239], v245 offset:17920
	ds_read_b64_tr_b16 v[240:241], v245 offset:19968
	s_add_i32 s41, s85, s24
	s_add_i32 m0, s41, 0xe000
	s_nop 0
	global_load_lds_dwordx4 v243, s[2:3]
	s_waitcnt lgkmcnt(8)
	v_mfma_f32_32x32x16_bf16 v[48:63], v[226:229], v[144:147], v[48:63]
	v_mfma_f32_32x32x16_bf16 v[32:47], v[226:229], v[148:151], v[32:47]
	ds_read_b64_tr_b16 v[144:145], v245 offset:21504
	ds_read_b64_tr_b16 v[146:147], v245 offset:23552
	ds_read_b64_tr_b16 v[148:149], v245 offset:22016
	ds_read_b64_tr_b16 v[150:151], v245 offset:24064
	s_waitcnt lgkmcnt(8)
	v_mfma_f32_32x32x16_bf16 v[48:63], v[230:233], v[152:155], v[48:63]
	v_mfma_f32_32x32x16_bf16 v[32:47], v[230:233], v[156:159], v[32:47]
	s_waitcnt lgkmcnt(0)
	v_mfma_f32_32x32x16_bf16 v[16:31], v[226:229], v[234:237], v[16:31]
	s_waitcnt vmcnt(0)
	s_barrier
; #define SBAR() __builtin_amdgcn_sched_barrier(0)
; #define PVR(S, DA, DB, vbase) do { S[0] = tr_read<v_rd_off(DA, 0, 0)>(vbase); S[1] = tr_read<v_rd_off(DA, 0, 1)>(vbase); S[2] = tr_read<v_rd_off(DB, 0, 0)>(vbase); S[3] = tr_read<v_rd_off(DB, 0, 1)>(vbase); \
;     S[4] = tr_read<v_rd_off(DA, 1, 0)>(vbase); S[5] = tr_read<v_rd_off(DA, 1, 1)>(vbase); S[6] = tr_read<v_rd_off(DB, 1, 0)>(vbase); S[7] = tr_read<v_rd_off(DB, 1, 1)>(vbase); } while (0)
; #define RAWBAR() do { asm volatile("s_waitcnt lgkmcnt(0)" ::: "memory"); __builtin_amdgcn_s_barrier(); asm volatile("" ::: "memory"); } while (0)
; #define RAWBAR() do { asm volatile("s_waitcnt lgkmcnt(0)" ::: "memory"); __builtin_amdgcn_s_barrier(); asm volatile("" ::: "memory"); } while (0)
; #define RAWBAR() do { asm volatile("s_waitcnt lgkmcnt(0)" ::: "memory"); __builtin_amdgcn_s_barrier(); asm volatile("" ::: "memory"); } while (0)
; #define RAWBAR() do { asm volatile("s_waitcnt lgkmcnt(0)" ::: "memory"); __builtin_amdgcn_s_barrier(); asm volatile("" ::: "memory"); } while (0)
; #define RAWBAR() do { asm volatile("s_waitcnt lgkmcnt(0)" ::: "memory"); __builtin_amdgcn_s_barrier(); asm volatile("" ::: "memory"); } while (0)
; template <int MODE> ...
;     ...
;   for (int j = 0; j < NT; ++j) {
;     const int buf = j & 1;
;     if (j + 1 < NT) { STAGE((j + 1) * KVBLK, buf ^ 1); }
;     const char* Kb = K_lds + buf * 16384;
;     f32x16 pe = {}, po = {};
; #pragma unroll
;     for (int d0 = 0; d0 < 8; d0 += 2) {
;       const bf16x8 k0 = *reinterpret_cast<const bf16x8*>(Kb + KSWZ(krow, (d0 * 16 + hi * 8) * 2));
;       const bf16x8 k1 = *reinterpret_cast<const bf16x8*>(Kb + KSWZ(krow, ((d0 + 1) * 16 + hi * 8) * 2));
;       pe = __builtin_amdgcn_mfma_f32_32x32x16_bf16(k0, qr[d0], pe, 0, 0, 0);
;       po = __builtin_amdgcn_mfma_f32_32x32x16_bf16(k1, qr[d0 + 1], po, 0, 0, 0); }
;     const int vo = vb0 + buf * 32768;
;     s16x4 R0_[8], R1_[8];
;     PVR(R0_, 0, 1, vo);
;     f32x16 p;
; #pragma unroll
;     for (int r = 0; r < 16; ++r) p[r] = __builtin_amdgcn_exp2f(fmaf(pe[r] + po[r], C, negMc));
;     float ps = 0.f;
; #pragma unroll
;     for (int r = 0; r < 16; ++r) ps += p[r];
;     lsum += ps;
;     const bf16x8 own0 = pk8(p, 0), own1 = pk8(p, 8);
;     SBAR();
;     PV_TAIL4(o, vo, vo + 16384, own0, own1);
;     asm volatile("s_waitcnt vmcnt(0)" ::: "memory");
;     RAWBAR();
	s_add_u32 s86, s86, 0x4000
	s_addc_u32 s87, s87, 0
	s_add_u32 s2, s2, 0x8000
	s_addc_u32 s3, s3, 0
	v_mfma_f32_32x32x16_bf16 v[0:15], v[226:229], v[238:241], v[0:15]
	v_mfma_f32_32x32x16_bf16 v[16:31], v[230:233], v[144:147], v[16:31]
	v_mfma_f32_32x32x16_bf16 v[0:15], v[230:233], v[148:151], v[0:15]
	s_add_i32 s84, s84, 0x8000
	s_cmp_eq_u32 s84, 0x18000
	s_cselect_b32 s84, 0, s84
	ds_read_b128 v[226:229], v225 offset:0
	ds_read_b128 v[230:233], v223 offset:0
	ds_read_b128 v[234:237], v222 offset:0
	ds_read_b128 v[238:241], v221 offset:0
	s_add_i32 m0, s24, 0x4000
	s_nop 0
	global_load_lds_dwordx4 v220, s[86:87]
	s_add_i32 m0, s24, 0x6000
	s_nop 0
	global_load_lds_dwordx4 v219, s[86:87]
	v_exp_f32_e32 v128, v128
	v_exp_f32_e32 v129, v129
	v_exp_f32_e32 v130, v130
	v_exp_f32_e32 v131, v131
	s_waitcnt lgkmcnt(2)
	v_mfma_f32_32x32x16_bf16 v[144:159], v[226:229], v[188:191], 0
	v_mfma_f32_32x32x16_bf16 v[144:159], v[230:233], v[184:187], v[144:159]
	ds_read_b128 v[226:229], v225 offset:128
	ds_read_b128 v[230:233], v223 offset:128
	v_exp_f32_e32 v132, v132
	v_exp_f32_e32 v133, v133
	v_exp_f32_e32 v134, v134
	v_exp_f32_e32 v135, v135
	v_add_f32_e32 v246, v128, v129
	v_add_f32_e32 v246, v130, v246
	v_add_f32_e32 v246, v131, v246
	s_waitcnt lgkmcnt(2)
	v_mfma_f32_32x32x16_bf16 v[144:159], v[234:237], v[180:183], v[144:159]
	v_mfma_f32_32x32x16_bf16 v[144:159], v[238:241], v[176:179], v[144:159]
	ds_read_b128 v[234:237], v222 offset:128
	ds_read_b128 v[238:241], v221 offset:128
	v_exp_f32_e32 v136, v136
	v_exp_f32_e32 v137, v137
	v_exp_f32_e32 v138, v138
	v_exp_f32_e32 v139, v139
	v_add_f32_e32 v246, v132, v246
	v_add_f32_e32 v246, v133, v246
	v_add_f32_e32 v246, v134, v246
	v_add_f32_e32 v246, v135, v246
	s_waitcnt lgkmcnt(2)
	v_mfma_f32_32x32x16_bf16 v[144:159], v[226:229], v[172:175], v[144:159]
	v_mfma_f32_32x32x16_bf16 v[144:159], v[230:233], v[168:171], v[144:159]
	v_exp_f32_e32 v140, v140
	v_exp_f32_e32 v141, v141
	v_exp_f32_e32 v142, v142
	v_exp_f32_e32 v143, v143
	v_add_f32_e32 v246, v136, v246
	v_add_f32_e32 v246, v137, v246
	v_add_f32_e32 v246, v138, v246
	v_add_f32_e32 v246, v139, v246
	v_cvt_pk_bf16_f32 v226, v128, v129
	v_cvt_pk_bf16_f32 v227, v130, v131
	v_cvt_pk_bf16_f32 v228, v132, v133
	v_cvt_pk_bf16_f32 v229, v134, v135
	s_waitcnt lgkmcnt(0)
	v_mfma_f32_32x32x16_bf16 v[144:159], v[234:237], v[164:167], v[144:159]
	v_mfma_f32_32x32x16_bf16 v[144:159], v[238:241], v[160:163], v[144:159]
	v_add_u32_e32 v245, s84, v214
	s_add_i32 s85, s84, 0x8000
	s_cmp_eq_u32 s85, 0x18000
	s_cselect_b32 s85, 0, s85
	ds_read_b64_tr_b16 v[234:235], v245 offset:0
	ds_read_b64_tr_b16 v[236:237], v245 offset:2048
	ds_read_b64_tr_b16 v[238:239], v245 offset:512
	ds_read_b64_tr_b16 v[240:241], v245 offset:2560
	ds_read_b64_tr_b16 v[128:129], v245 offset:4096
	ds_read_b64_tr_b16 v[130:131], v245 offset:6144
	ds_read_b64_tr_b16 v[132:133], v245 offset:4608
	ds_read_b64_tr_b16 v[134:135], v245 offset:6656
	v_add_f32_e32 v246, v140, v246
	v_add_f32_e32 v246, v141, v246
	v_add_f32_e32 v246, v142, v246
	v_add_f32_e32 v246, v143, v246
	v_cvt_pk_bf16_f32 v230, v136, v137
	v_cvt_pk_bf16_f32 v231, v138, v139
	v_cvt_pk_bf16_f32 v232, v140, v141
	v_cvt_pk_bf16_f32 v233, v142, v143
	v_add_f32_e32 v215, v215, v246
	ds_read_b64_tr_b16 v[136:137], v245 offset:1024
	ds_read_b64_tr_b16 v[138:139], v245 offset:3072
	ds_read_b64_tr_b16 v[140:141], v245 offset:1536
	ds_read_b64_tr_b16 v[142:143], v245 offset:3584
	s_waitcnt lgkmcnt(8)
	v_mfma_f32_32x32x16_bf16 v[112:127], v[226:229], v[234:237], v[112:127]
	v_mfma_f32_32x32x16_bf16 v[96:111], v[226:229], v[238:241], v[96:111]
	ds_read_b64_tr_b16 v[234:235], v245 offset:5120
	ds_read_b64_tr_b16 v[236:237], v245 offset:7168
	ds_read_b64_tr_b16 v[238:239], v245 offset:5632
	ds_read_b64_tr_b16 v[240:241], v245 offset:7680
	s_add_i32 s41, s85, s24
	s_add_i32 m0, s41, 0x8000
	s_nop 0
	global_load_lds_dwordx4 v218, s[2:3]
	s_waitcnt lgkmcnt(8)
	v_mfma_f32_32x32x16_bf16 v[112:127], v[230:233], v[128:131], v[112:127]
	v_mfma_f32_32x32x16_bf16 v[96:111], v[230:233], v[132:135], v[96:111]
	ds_read_b64_tr_b16 v[128:129], v245 offset:16384
	ds_read_b64_tr_b16 v[130:131], v245 offset:18432
	ds_read_b64_tr_b16 v[132:133], v245 offset:16896
	ds_read_b64_tr_b16 v[134:135], v245 offset:18944
	s_add_i32 s41, s85, s24
	s_add_i32 m0, s41, 0xa000
	s_nop 0
	global_load_lds_dwordx4 v217, s[2:3]
	s_waitcnt lgkmcnt(8)
	v_mfma_f32_32x32x16_bf16 v[80:95], v[226:229], v[136:139], v[80:95]
	v_mfma_f32_32x32x16_bf16 v[64:79], v[226:229], v[140:143], v[64:79]
	ds_read_b64_tr_b16 v[136:137], v245 offset:20480
	ds_read_b64_tr_b16 v[138:139], v245 offset:22528
	ds_read_b64_tr_b16 v[140:141], v245 offset:20992
	ds_read_b64_tr_b16 v[142:143], v245 offset:23040
	s_add_i32 s41, s85, s24
	s_add_i32 m0, s41, 0xc000
	s_nop 0
	global_load_lds_dwordx4 v242, s[2:3]
	s_waitcnt lgkmcnt(8)
	v_mfma_f32_32x32x16_bf16 v[80:95], v[230:233], v[234:237], v[80:95]
	v_mfma_f32_32x32x16_bf16 v[64:79], v[230:233], v[238:241], v[64:79]
	ds_read_b64_tr_b16 v[234:235], v245 offset:17408
	ds_read_b64_tr_b16 v[236:237], v245 offset:19456
	ds_read_b64_tr_b16 v[238:239], v245 offset:17920
	ds_read_b64_tr_b16 v[240:241], v245 offset:19968
	s_add_i32 s41, s85, s24
	s_add_i32 m0, s41, 0xe000
	s_nop 0
	global_load_lds_dwordx4 v243, s[2:3]
	s_waitcnt lgkmcnt(8)
	v_mfma_f32_32x32x16_bf16 v[48:63], v[226:229], v[128:131], v[48:63]
	v_mfma_f32_32x32x16_bf16 v[32:47], v[226:229], v[132:135], v[32:47]
	ds_read_b64_tr_b16 v[128:129], v245 offset:21504
	ds_read_b64_tr_b16 v[130:131], v245 offset:23552
	ds_read_b64_tr_b16 v[132:133], v245 offset:22016
	ds_read_b64_tr_b16 v[134:135], v245 offset:24064
	s_waitcnt lgkmcnt(8)
	v_mfma_f32_32x32x16_bf16 v[48:63], v[230:233], v[136:139], v[48:63]
	v_mfma_f32_32x32x16_bf16 v[32:47], v[230:233], v[140:143], v[32:47]
	s_waitcnt lgkmcnt(0)
	v_mfma_f32_32x32x16_bf16 v[16:31], v[226:229], v[234:237], v[16:31]
	s_waitcnt vmcnt(0)
	s_barrier
	s_add_u32 s86, s86, 0x4000
	s_addc_u32 s87, s87, 0
	s_add_u32 s2, s2, 0x8000
	s_addc_u32 s3, s3, 0
	v_mfma_f32_32x32x16_bf16 v[0:15], v[226:229], v[238:241], v[0:15]
	v_mfma_f32_32x32x16_bf16 v[16:31], v[230:233], v[128:131], v[16:31]
	v_mfma_f32_32x32x16_bf16 v[0:15], v[230:233], v[132:135], v[0:15]
	s_add_i32 s84, s84, 0x8000
	s_cmp_eq_u32 s84, 0x18000
	s_cselect_b32 s84, 0, s84
	s_add_i32 s25, s25, 1
	s_cmpk_eq_i32 s25, 0x82
	s_cbranch_scc0 .LBB0_1019
	s_barrier
	s_branch .Lattn_join_m0

; #define SBAR() __builtin_amdgcn_sched_barrier(0)
; #define PVR(S, DA, DB, vbase) do { S[0] = tr_read<v_rd_off(DA, 0, 0)>(vbase); S[1] = tr_read<v_rd_off(DA, 0, 1)>(vbase); S[2] = tr_read<v_rd_off(DB, 0, 0)>(vbase); S[3] = tr_read<v_rd_off(DB, 0, 1)>(vbase); \
;     S[4] = tr_read<v_rd_off(DA, 1, 0)>(vbase); S[5] = tr_read<v_rd_off(DA, 1, 1)>(vbase); S[6] = tr_read<v_rd_off(DB, 1, 0)>(vbase); S[7] = tr_read<v_rd_off(DB, 1, 1)>(vbase); } while (0)
; #define RAWBAR() do { asm volatile("s_waitcnt lgkmcnt(0)" ::: "memory"); __builtin_amdgcn_s_barrier(); asm volatile("" ::: "memory"); } while (0)
; #define RAWBAR() do { asm volatile("s_waitcnt lgkmcnt(0)" ::: "memory"); __builtin_amdgcn_s_barrier(); asm volatile("" ::: "memory"); } while (0)
; #define RAWBAR() do { asm volatile("s_waitcnt lgkmcnt(0)" ::: "memory"); __builtin_amdgcn_s_barrier(); asm volatile("" ::: "memory"); } while (0)
; #define RAWBAR() do { asm volatile("s_waitcnt lgkmcnt(0)" ::: "memory"); __builtin_amdgcn_s_barrier(); asm volatile("" ::: "memory"); } while (0)
; #define RAWBAR() do { asm volatile("s_waitcnt lgkmcnt(0)" ::: "memory"); __builtin_amdgcn_s_barrier(); asm volatile("" ::: "memory"); } while (0)
; template <int MODE> ...
;     ...
;   for (int j = 0; j < NT; ++j) {
;     const int buf = j & 1;
;     if (j + 1 < NT) { STAGE((j + 1) * KVBLK, buf ^ 1); }
;     const char* Kb = K_lds + buf * 16384;
;     f32x16 pe = {}, po = {};
; #pragma unroll
;     for (int d0 = 0; d0 < 8; d0 += 2) {
;       const bf16x8 k0 = *reinterpret_cast<const bf16x8*>(Kb + KSWZ(krow, (d0 * 16 + hi * 8) * 2));
;       const bf16x8 k1 = *reinterpret_cast<const bf16x8*>(Kb + KSWZ(krow, ((d0 + 1) * 16 + hi * 8) * 2));
;       pe = __builtin_amdgcn_mfma_f32_32x32x16_bf16(k0, qr[d0], pe, 0, 0, 0);
;       po = __builtin_amdgcn_mfma_f32_32x32x16_bf16(k1, qr[d0 + 1], po, 0, 0, 0); }
;     const int vo = vb0 + buf * 32768;
;     s16x4 R0_[8], R1_[8];
;     PVR(R0_, 0, 1, vo);
;     f32x16 p;
; #pragma unroll
;     for (int r = 0; r < 16; ++r) p[r] = __builtin_amdgcn_exp2f(fmaf(pe[r] + po[r], C, negMc));
;     float ps = 0.f;
; #pragma unroll
;     for (int r = 0; r < 16; ++r) ps += p[r];
;     lsum += ps;
;     const bf16x8 own0 = pk8(p, 0), own1 = pk8(p, 8);
;     SBAR();
;     PV_TAIL4(o, vo, vo + 16384, own0, own1);
;     asm volatile("s_waitcnt vmcnt(0)" ::: "memory");
;     RAWBAR();
.LattnB_m0:
	ds_read_b128 v[226:229], v225 offset:16384
	ds_read_b128 v[230:233], v223 offset:16384
	ds_read_b128 v[234:237], v222 offset:16384
	ds_read_b128 v[238:241], v221 offset:16384
	v_exp_f32_e32 v144, v144
	v_exp_f32_e32 v145, v145
	v_exp_f32_e32 v146, v146
	v_exp_f32_e32 v147, v147
	s_waitcnt lgkmcnt(2)
	v_mfma_f32_32x32x16_bf16 v[128:143], v[226:229], v[188:191], 0
	v_mfma_f32_32x32x16_bf16 v[128:143], v[230:233], v[184:187], v[128:143]
	ds_read_b128 v[226:229], v225 offset:16512
	ds_read_b128 v[230:233], v223 offset:16512
	v_exp_f32_e32 v148, v148
	v_exp_f32_e32 v149, v149
	v_exp_f32_e32 v150, v150
	v_exp_f32_e32 v151, v151
	v_add_f32_e32 v246, v144, v145
	v_add_f32_e32 v246, v146, v246
	v_add_f32_e32 v246, v147, v246
	s_waitcnt lgkmcnt(2)
	v_mfma_f32_32x32x16_bf16 v[128:143], v[234:237], v[180:183], v[128:143]
	v_mfma_f32_32x32x16_bf16 v[128:143], v[238:241], v[176:179], v[128:143]
	ds_read_b128 v[234:237], v222 offset:16512
	ds_read_b128 v[238:241], v221 offset:16512
	v_exp_f32_e32 v152, v152
	v_exp_f32_e32 v153, v153
	v_exp_f32_e32 v154, v154
	v_exp_f32_e32 v155, v155
	v_add_f32_e32 v246, v148, v246
	v_add_f32_e32 v246, v149, v246
	v_add_f32_e32 v246, v150, v246
	v_add_f32_e32 v246, v151, v246
	s_waitcnt lgkmcnt(2)
	v_mfma_f32_32x32x16_bf16 v[128:143], v[226:229], v[172:175], v[128:143]
	v_mfma_f32_32x32x16_bf16 v[128:143], v[230:233], v[168:171], v[128:143]
	v_exp_f32_e32 v156, v156
	v_exp_f32_e32 v157, v157
	v_exp_f32_e32 v158, v158
	v_exp_f32_e32 v159, v159
	v_add_f32_e32 v246, v152, v246
	v_add_f32_e32 v246, v153, v246
	v_add_f32_e32 v246, v154, v246
	v_add_f32_e32 v246, v155, v246
	v_cvt_pk_bf16_f32 v226, v144, v145
	v_cvt_pk_bf16_f32 v227, v146, v147
	v_cvt_pk_bf16_f32 v228, v148, v149
	v_cvt_pk_bf16_f32 v229, v150, v151
	s_waitcnt lgkmcnt(0)
	v_mfma_f32_32x32x16_bf16 v[128:143], v[234:237], v[164:167], v[128:143]
	v_mfma_f32_32x32x16_bf16 v[128:143], v[238:241], v[160:163], v[128:143]
	s_waitcnt vmcnt(0)
	s_barrier
	s_add_u32 s86, s86, 0x4000
	s_addc_u32 s87, s87, 0
	s_add_u32 s2, s2, 0x8000
	s_addc_u32 s3, s3, 0
	s_add_i32 m0, s24, 0x4000
	s_nop 0
	global_load_lds_dwordx4 v220, s[86:87]
	s_add_i32 m0, s24, 0x6000
	s_nop 0
	global_load_lds_dwordx4 v219, s[86:87]
	v_add_u32_e32 v245, s84, v214
	s_sub_u32 s85, s84, 0x8000
	s_cmp_eq_u32 s84, 0
	s_cselect_b32 s85, 0x10000, s85
	ds_read_b64_tr_b16 v[234:235], v245 offset:0
	ds_read_b64_tr_b16 v[236:237], v245 offset:2048
	ds_read_b64_tr_b16 v[238:239], v245 offset:512
	ds_read_b64_tr_b16 v[240:241], v245 offset:2560
	ds_read_b64_tr_b16 v[144:145], v245 offset:4096
	ds_read_b64_tr_b16 v[146:147], v245 offset:6144
	ds_read_b64_tr_b16 v[148:149], v245 offset:4608
	ds_read_b64_tr_b16 v[150:151], v245 offset:6656
	v_add_f32_e32 v246, v156, v246
	v_add_f32_e32 v246, v157, v246
	v_add_f32_e32 v246, v158, v246
	v_add_f32_e32 v246, v159, v246
	v_cvt_pk_bf16_f32 v230, v152, v153
	v_cvt_pk_bf16_f32 v231, v154, v155
	v_cvt_pk_bf16_f32 v232, v156, v157
	v_cvt_pk_bf16_f32 v233, v158, v159
	v_add_f32_e32 v215, v215, v246
	ds_read_b64_tr_b16 v[152:153], v245 offset:1024
	ds_read_b64_tr_b16 v[154:155], v245 offset:3072
	ds_read_b64_tr_b16 v[156:157], v245 offset:1536
	ds_read_b64_tr_b16 v[158:159], v245 offset:3584
	s_waitcnt lgkmcnt(8)
	v_mfma_f32_32x32x16_bf16 v[112:127], v[226:229], v[234:237], v[112:127]
	v_mfma_f32_32x32x16_bf16 v[96:111], v[226:229], v[238:241], v[96:111]
	ds_read_b64_tr_b16 v[234:235], v245 offset:5120
	ds_read_b64_tr_b16 v[236:237], v245 offset:7168
	ds_read_b64_tr_b16 v[238:239], v245 offset:5632
	ds_read_b64_tr_b16 v[240:241], v245 offset:7680
	s_add_i32 s41, s85, s24
	s_add_i32 m0, s41, 0x8000
	s_nop 0
	global_load_lds_dwordx4 v218, s[2:3]
	s_waitcnt lgkmcnt(8)
	v_mfma_f32_32x32x16_bf16 v[112:127], v[230:233], v[144:147], v[112:127]
	v_mfma_f32_32x32x16_bf16 v[96:111], v[230:233], v[148:151], v[96:111]
	ds_read_b64_tr_b16 v[144:145], v245 offset:16384
	ds_read_b64_tr_b16 v[146:147], v245 offset:18432
	ds_read_b64_tr_b16 v[148:149], v245 offset:16896
	ds_read_b64_tr_b16 v[150:151], v245 offset:18944
	s_add_i32 s41, s85, s24
	s_add_i32 m0, s41, 0xa000
	s_nop 0
	global_load_lds_dwordx4 v217, s[2:3]
	s_waitcnt lgkmcnt(8)
	v_mfma_f32_32x32x16_bf16 v[80:95], v[226:229], v[152:155], v[80:95]
	v_mfma_f32_32x32x16_bf16 v[64:79], v[226:229], v[156:159], v[64:79]
	ds_read_b64_tr_b16 v[152:153], v245 offset:20480
	ds_read_b64_tr_b16 v[154:155], v245 offset:22528
	ds_read_b64_tr_b16 v[156:157], v245 offset:20992
	ds_read_b64_tr_b16 v[158:159], v245 offset:23040
	s_add_i32 s41, s85, s24
	s_add_i32 m0, s41, 0xc000
	s_nop 0
	global_load_lds_dwordx4 v242, s[2:3]
	s_waitcnt lgkmcnt(8)
	v_mfma_f32_32x32x16_bf16 v[80:95], v[230:233], v[234:237], v[80:95]
	v_mfma_f32_32x32x16_bf16 v[64:79], v[230:233], v[238:241], v[64:79]
	ds_read_b64_tr_b16 v[234:235], v245 offset:17408
	ds_read_b64_tr_b16 v[236:237], v245 offset:19456
	ds_read_b64_tr_b16 v[238:239], v245 offset:17920
	ds_read_b64_tr_b16 v[240:241], v245 offset:19968
	s_add_i32 s41, s85, s24
	s_add_i32 m0, s41, 0xe000
	s_nop 0
	global_load_lds_dwordx4 v243, s[2:3]
	s_waitcnt lgkmcnt(8)
	v_mfma_f32_32x32x16_bf16 v[48:63], v[226:229], v[144:147], v[48:63]
	v_mfma_f32_32x32x16_bf16 v[32:47], v[226:229], v[148:151], v[32:47]
	ds_read_b64_tr_b16 v[144:145], v245 offset:21504
	ds_read_b64_tr_b16 v[146:147], v245 offset:23552
	ds_read_b64_tr_b16 v[148:149], v245 offset:22016
	ds_read_b64_tr_b16 v[150:151], v245 offset:24064
	s_waitcnt lgkmcnt(8)
	v_mfma_f32_32x32x16_bf16 v[48:63], v[230:233], v[152:155], v[48:63]
	v_mfma_f32_32x32x16_bf16 v[32:47], v[230:233], v[156:159], v[32:47]
	s_waitcnt lgkmcnt(0)
; #define SBAR() __builtin_amdgcn_sched_barrier(0)
; #define PVR(S, DA, DB, vbase) do { S[0] = tr_read<v_rd_off(DA, 0, 0)>(vbase); S[1] = tr_read<v_rd_off(DA, 0, 1)>(vbase); S[2] = tr_read<v_rd_off(DB, 0, 0)>(vbase); S[3] = tr_read<v_rd_off(DB, 0, 1)>(vbase); \
;     S[4] = tr_read<v_rd_off(DA, 1, 0)>(vbase); S[5] = tr_read<v_rd_off(DA, 1, 1)>(vbase); S[6] = tr_read<v_rd_off(DB, 1, 0)>(vbase); S[7] = tr_read<v_rd_off(DB, 1, 1)>(vbase); } while (0)
; #define RAWBAR() do { asm volatile("s_waitcnt lgkmcnt(0)" ::: "memory"); __builtin_amdgcn_s_barrier(); asm volatile("" ::: "memory"); } while (0)
; #define RAWBAR() do { asm volatile("s_waitcnt lgkmcnt(0)" ::: "memory"); __builtin_amdgcn_s_barrier(); asm volatile("" ::: "memory"); } while (0)
; #define RAWBAR() do { asm volatile("s_waitcnt lgkmcnt(0)" ::: "memory"); __builtin_amdgcn_s_barrier(); asm volatile("" ::: "memory"); } while (0)
; #define RAWBAR() do { asm volatile("s_waitcnt lgkmcnt(0)" ::: "memory"); __builtin_amdgcn_s_barrier(); asm volatile("" ::: "memory"); } while (0)
; #define RAWBAR() do { asm volatile("s_waitcnt lgkmcnt(0)" ::: "memory"); __builtin_amdgcn_s_barrier(); asm volatile("" ::: "memory"); } while (0)
; template <int MODE> ...
;     ...
;   for (int j = 0; j < NT; ++j) {
;     const int buf = j & 1;
;     if (j + 1 < NT) { STAGE((j + 1) * KVBLK, buf ^ 1); }
;     const char* Kb = K_lds + buf * 16384;
;     f32x16 pe = {}, po = {};
; #pragma unroll
;     for (int d0 = 0; d0 < 8; d0 += 2) {
;       const bf16x8 k0 = *reinterpret_cast<const bf16x8*>(Kb + KSWZ(krow, (d0 * 16 + hi * 8) * 2));
;       const bf16x8 k1 = *reinterpret_cast<const bf16x8*>(Kb + KSWZ(krow, ((d0 + 1) * 16 + hi * 8) * 2));
;       pe = __builtin_amdgcn_mfma_f32_32x32x16_bf16(k0, qr[d0], pe, 0, 0, 0);
;       po = __builtin_amdgcn_mfma_f32_32x32x16_bf16(k1, qr[d0 + 1], po, 0, 0, 0); }
;     const int vo = vb0 + buf * 32768;
;     s16x4 R0_[8], R1_[8];
;     PVR(R0_, 0, 1, vo);
;     f32x16 p;
; #pragma unroll
;     for (int r = 0; r < 16; ++r) p[r] = __builtin_amdgcn_exp2f(fmaf(pe[r] + po[r], C, negMc));
;     float ps = 0.f;
; #pragma unroll
;     for (int r = 0; r < 16; ++r) ps += p[r];
;     lsum += ps;
;     const bf16x8 own0 = pk8(p, 0), own1 = pk8(p, 8);
;     SBAR();
;     PV_TAIL4(o, vo, vo + 16384, own0, own1);
;     asm volatile("s_waitcnt vmcnt(0)" ::: "memory");
;     RAWBAR();
	v_mfma_f32_32x32x16_bf16 v[16:31], v[226:229], v[234:237], v[16:31]
	v_mfma_f32_32x32x16_bf16 v[0:15], v[226:229], v[238:241], v[0:15]
	v_mfma_f32_32x32x16_bf16 v[16:31], v[230:233], v[144:147], v[16:31]
	v_mfma_f32_32x32x16_bf16 v[0:15], v[230:233], v[148:151], v[0:15]
	s_add_i32 s84, s84, 0x8000
	s_cmp_eq_u32 s84, 0x18000
	s_cselect_b32 s84, 0, s84
	ds_read_b128 v[226:229], v225 offset:0
	ds_read_b128 v[230:233], v223 offset:0
	ds_read_b128 v[234:237], v222 offset:0
	ds_read_b128 v[238:241], v221 offset:0
	v_exp_f32_e32 v128, v128
	v_exp_f32_e32 v129, v129
	v_exp_f32_e32 v130, v130
	v_exp_f32_e32 v131, v131
	s_waitcnt lgkmcnt(2)
	v_mfma_f32_32x32x16_bf16 v[144:159], v[226:229], v[188:191], 0
	v_mfma_f32_32x32x16_bf16 v[144:159], v[230:233], v[184:187], v[144:159]
	ds_read_b128 v[226:229], v225 offset:128
	ds_read_b128 v[230:233], v223 offset:128
	v_exp_f32_e32 v132, v132
	v_exp_f32_e32 v133, v133
	v_exp_f32_e32 v134, v134
	v_exp_f32_e32 v135, v135
	v_add_f32_e32 v246, v128, v129
	v_add_f32_e32 v246, v130, v246
	v_add_f32_e32 v246, v131, v246
	s_waitcnt lgkmcnt(2)
	v_mfma_f32_32x32x16_bf16 v[144:159], v[234:237], v[180:183], v[144:159]
	v_mfma_f32_32x32x16_bf16 v[144:159], v[238:241], v[176:179], v[144:159]
	ds_read_b128 v[234:237], v222 offset:128
	ds_read_b128 v[238:241], v221 offset:128
	v_exp_f32_e32 v136, v136
	v_exp_f32_e32 v137, v137
	v_exp_f32_e32 v138, v138
	v_exp_f32_e32 v139, v139
	v_add_f32_e32 v246, v132, v246
	v_add_f32_e32 v246, v133, v246
	v_add_f32_e32 v246, v134, v246
	v_add_f32_e32 v246, v135, v246
	s_waitcnt lgkmcnt(2)
	v_mfma_f32_32x32x16_bf16 v[144:159], v[226:229], v[172:175], v[144:159]
	v_mfma_f32_32x32x16_bf16 v[144:159], v[230:233], v[168:171], v[144:159]
	v_exp_f32_e32 v140, v140
	v_exp_f32_e32 v141, v141
	v_exp_f32_e32 v142, v142
	v_exp_f32_e32 v143, v143
	v_add_f32_e32 v246, v136, v246
	v_add_f32_e32 v246, v137, v246
	v_add_f32_e32 v246, v138, v246
	v_add_f32_e32 v246, v139, v246
	v_cvt_pk_bf16_f32 v226, v128, v129
	v_cvt_pk_bf16_f32 v227, v130, v131
	v_cvt_pk_bf16_f32 v228, v132, v133
	v_cvt_pk_bf16_f32 v229, v134, v135
	s_waitcnt lgkmcnt(0)
	v_mfma_f32_32x32x16_bf16 v[144:159], v[234:237], v[164:167], v[144:159]
	v_mfma_f32_32x32x16_bf16 v[144:159], v[238:241], v[160:163], v[144:159]
	s_waitcnt vmcnt(0)
	s_barrier
	s_add_u32 s86, s86, 0x4000
	s_addc_u32 s87, s87, 0
	s_add_u32 s2, s2, 0x8000
	s_addc_u32 s3, s3, 0
	s_mov_b32 m0, s24
	s_nop 0
	global_load_lds_dwordx4 v220, s[86:87]
	s_add_i32 m0, s24, 0x2000
	s_nop 0
	global_load_lds_dwordx4 v219, s[86:87]
	v_add_u32_e32 v245, s84, v214
	s_sub_u32 s85, s84, 0x8000
	s_cmp_eq_u32 s84, 0
	s_cselect_b32 s85, 0x10000, s85
	ds_read_b64_tr_b16 v[234:235], v245 offset:0
	ds_read_b64_tr_b16 v[236:237], v245 offset:2048
	ds_read_b64_tr_b16 v[238:239], v245 offset:512
	ds_read_b64_tr_b16 v[240:241], v245 offset:2560
	ds_read_b64_tr_b16 v[128:129], v245 offset:4096
	ds_read_b64_tr_b16 v[130:131], v245 offset:6144
	ds_read_b64_tr_b16 v[132:133], v245 offset:4608
	ds_read_b64_tr_b16 v[134:135], v245 offset:6656
	v_add_f32_e32 v246, v140, v246
	v_add_f32_e32 v246, v141, v246
	v_add_f32_e32 v246, v142, v246
	v_add_f32_e32 v246, v143, v246
	v_cvt_pk_bf16_f32 v230, v136, v137
	v_cvt_pk_bf16_f32 v231, v138, v139
	v_cvt_pk_bf16_f32 v232, v140, v141
	v_cvt_pk_bf16_f32 v233, v142, v143
	v_add_f32_e32 v215, v215, v246
	ds_read_b64_tr_b16 v[136:137], v245 offset:1024
	ds_read_b64_tr_b16 v[138:139], v245 offset:3072
	ds_read_b64_tr_b16 v[140:141], v245 offset:1536
	ds_read_b64_tr_b16 v[142:143], v245 offset:3584
	s_waitcnt lgkmcnt(8)
	v_mfma_f32_32x32x16_bf16 v[112:127], v[226:229], v[234:237], v[112:127]
	v_mfma_f32_32x32x16_bf16 v[96:111], v[226:229], v[238:241], v[96:111]
	ds_read_b64_tr_b16 v[234:235], v245 offset:5120
	ds_read_b64_tr_b16 v[236:237], v245 offset:7168
	ds_read_b64_tr_b16 v[238:239], v245 offset:5632
	ds_read_b64_tr_b16 v[240:241], v245 offset:7680
	s_add_i32 s41, s85, s24
	s_add_i32 m0, s41, 0x8000
	s_nop 0
	global_load_lds_dwordx4 v218, s[2:3]
	s_waitcnt lgkmcnt(8)
	v_mfma_f32_32x32x16_bf16 v[112:127], v[230:233], v[128:131], v[112:127]
	v_mfma_f32_32x32x16_bf16 v[96:111], v[230:233], v[132:135], v[96:111]
	ds_read_b64_tr_b16 v[128:129], v245 offset:16384
	ds_read_b64_tr_b16 v[130:131], v245 offset:18432
	ds_read_b64_tr_b16 v[132:133], v245 offset:16896
	ds_read_b64_tr_b16 v[134:135], v245 offset:18944
	s_add_i32 s41, s85, s24
	s_add_i32 m0, s41, 0xa000
	s_nop 0
	global_load_lds_dwordx4 v217, s[2:3]
	s_waitcnt lgkmcnt(8)
	v_mfma_f32_32x32x16_bf16 v[80:95], v[226:229], v[136:139], v[80:95]
	v_mfma_f32_32x32x16_bf16 v[64:79], v[226:229], v[140:143], v[64:79]
	ds_read_b64_tr_b16 v[136:137], v245 offset:20480
	ds_read_b64_tr_b16 v[138:139], v245 offset:22528
	ds_read_b64_tr_b16 v[140:141], v245 offset:20992
	ds_read_b64_tr_b16 v[142:143], v245 offset:23040
	s_add_i32 s41, s85, s24
	s_add_i32 m0, s41, 0xc000
	s_nop 0
	global_load_lds_dwordx4 v242, s[2:3]
	s_waitcnt lgkmcnt(8)
	v_mfma_f32_32x32x16_bf16 v[80:95], v[230:233], v[234:237], v[80:95]
	v_mfma_f32_32x32x16_bf16 v[64:79], v[230:233], v[238:241], v[64:79]
	ds_read_b64_tr_b16 v[234:235], v245 offset:17408
	ds_read_b64_tr_b16 v[236:237], v245 offset:19456
	ds_read_b64_tr_b16 v[238:239], v245 offset:17920
	ds_read_b64_tr_b16 v[240:241], v245 offset:19968
	s_add_i32 s41, s85, s24
	s_add_i32 m0, s41, 0xe000
	s_nop 0
	global_load_lds_dwordx4 v243, s[2:3]
	s_waitcnt lgkmcnt(8)
	v_mfma_f32_32x32x16_bf16 v[48:63], v[226:229], v[128:131], v[48:63]
	v_mfma_f32_32x32x16_bf16 v[32:47], v[226:229], v[132:135], v[32:47]
	ds_read_b64_tr_b16 v[128:129], v245 offset:21504
	ds_read_b64_tr_b16 v[130:131], v245 offset:23552
	ds_read_b64_tr_b16 v[132:133], v245 offset:22016
	ds_read_b64_tr_b16 v[134:135], v245 offset:24064
	s_waitcnt lgkmcnt(8)
	v_mfma_f32_32x32x16_bf16 v[48:63], v[230:233], v[136:139], v[48:63]
	v_mfma_f32_32x32x16_bf16 v[32:47], v[230:233], v[140:143], v[32:47]
	s_waitcnt lgkmcnt(0)
	v_mfma_f32_32x32x16_bf16 v[16:31], v[226:229], v[234:237], v[16:31]
	v_mfma_f32_32x32x16_bf16 v[0:15], v[226:229], v[238:241], v[0:15]
	v_mfma_f32_32x32x16_bf16 v[16:31], v[230:233], v[128:131], v[16:31]
	v_mfma_f32_32x32x16_bf16 v[0:15], v[230:233], v[132:135], v[0:15]
	s_add_i32 s84, s84, 0x8000
	s_cmp_eq_u32 s84, 0x18000
	s_cselect_b32 s84, 0, s84
	s_add_i32 s25, s25, 1
	s_cmpk_eq_i32 s25, 0x82
	s_cbranch_scc0 .LattnB_m0
	s_waitcnt vmcnt(0)
	s_barrier

; __device__ __forceinline__ int crow(int r, int hi) { return (r & 3) + 8 * (r >> 2) + 4 * hi; }
; #define XS_WRITE(OV, BASE) do { float* xs_ = (float*)(lds + (BASE)) + ((g * 4) * 64 + lane) * 16; \
;     _Pragma("unroll") for (int d0 = 0; d0 < 4; ++d0) { float* xp = xs_ + d0 * 64 * 16; \
;       _Pragma("unroll") for (int q4 = 0; q4 < 4; ++q4) *(f32x4v*)(xp + 4 * q4) = (f32x4v){OV[d0][4 * q4], OV[d0][4 * q4 + 1], OV[d0][4 * q4 + 2], OV[d0][4 * q4 + 3]}; } } while (0)
; #define XS_WRITE(OV, BASE) do { float* xs_ = (float*)(lds + (BASE)) + ((g * 4) * 64 + lane) * 16; \
;     _Pragma("unroll") for (int d0 = 0; d0 < 4; ++d0) { float* xp = xs_ + d0 * 64 * 16; \
;       _Pragma("unroll") for (int q4 = 0; q4 < 4; ++q4) *(f32x4v*)(xp + 4 * q4) = (f32x4v){OV[d0][4 * q4], OV[d0][4 * q4 + 1], OV[d0][4 * q4 + 2], OV[d0][4 * q4 + 3]}; } } while (0)
; template <int MODE> ...
;     ...
;   __builtin_amdgcn_s_setprio(0);
;   L_lds[(wid * 2 + hi) * 32 + r32] = lsum;
;     ...
;   f32x16* olo = o; f32x16* ohi = o + 4;
;   if (kh) { XS_WRITE(olo, 0); } else { XS_WRITE(ohi, 65536); }
;   __syncthreads();
;   if (kh) { XS_ADD(ohi, 65536);
; #pragma unroll
;     for (int d0 = 0; d0 < 4; ++d0) o[d0] = o[4 + d0]; }
;   else { XS_ADD(olo, 0); }
;     ...
;   float rli[16];
; #pragma unroll
;   for (int r = 0; r < 16; ++r) { const int row = crow(r, hi); const float* lp = L_lds + (g * 4) * 32 + row; rli[r] = __builtin_amdgcn_rcpf((lp[0] + lp[32]) + (lp[64] + lp[96])); }
.LBB0_1022:
	s_or_b64 exec, exec, s[24:25]
	v_add3_u32 v80, v129, v128, v130
	ds_read_b128 v[64:67], v80
	ds_read_b128 v[68:71], v80 offset:16
	ds_read_b128 v[72:75], v80 offset:32
	ds_read_b128 v[76:79], v80 offset:48
	s_ashr_i32 s24, s40, 3
	s_ashr_i32 s25, s24, 31
	s_waitcnt lgkmcnt(2)
	v_add_f32_e32 v68, v52, v68
	v_add_f32_e32 v64, v48, v64
	v_add_f32_e32 v65, v49, v65
	v_add_f32_e32 v66, v50, v66
	v_add_f32_e32 v67, v51, v67
	ds_read_b128 v[48:51], v80 offset:4096
	v_add_f32_e32 v69, v53, v69
	v_add_f32_e32 v70, v54, v70
	v_add_f32_e32 v71, v55, v71
	ds_read_b128 v[52:55], v80 offset:4112
	s_waitcnt lgkmcnt(1)
	v_add_f32_e32 v48, v32, v48
	v_add_f32_e32 v49, v33, v49
	v_add_f32_e32 v50, v34, v50
	v_add_f32_e32 v51, v35, v51
	ds_read_b128 v[32:35], v80 offset:4128
	s_waitcnt lgkmcnt(1)
	v_add_f32_e32 v52, v36, v52
	v_add_f32_e32 v53, v37, v53
	v_add_f32_e32 v54, v38, v54
	v_add_f32_e32 v55, v39, v55
	ds_read_b128 v[36:39], v80 offset:4144
	s_waitcnt lgkmcnt(1)
	v_add_f32_e32 v40, v40, v32
	v_add_f32_e32 v41, v41, v33
	v_add_f32_e32 v42, v42, v34
	v_add_f32_e32 v43, v43, v35
	ds_read_b128 v[32:35], v80 offset:8192
	s_waitcnt lgkmcnt(1)
	v_add_f32_e32 v44, v44, v36
	v_add_f32_e32 v45, v45, v37
	v_add_f32_e32 v46, v46, v38
	v_add_f32_e32 v47, v47, v39
	ds_read_b128 v[36:39], v80 offset:8208
	s_waitcnt lgkmcnt(1)
	v_add_f32_e32 v32, v16, v32
	v_add_f32_e32 v33, v17, v33
	v_add_f32_e32 v34, v18, v34
	v_add_f32_e32 v35, v19, v35
	ds_read_b128 v[16:19], v80 offset:8224
	s_waitcnt lgkmcnt(1)
	v_add_f32_e32 v36, v20, v36
	v_add_f32_e32 v37, v21, v37
	v_add_f32_e32 v38, v22, v38
	v_add_f32_e32 v39, v23, v39
	ds_read_b128 v[20:23], v80 offset:8240
	v_add_f32_e32 v56, v56, v72
	v_add_f32_e32 v57, v57, v73
	v_add_f32_e32 v58, v58, v74
	v_add_f32_e32 v59, v59, v75
	s_waitcnt lgkmcnt(1)
	v_add_f32_e32 v72, v24, v16
	v_add_f32_e32 v73, v25, v17
	v_add_f32_e32 v74, v26, v18
	v_add_f32_e32 v75, v27, v19
	ds_read_b128 v[16:19], v80 offset:12288
	v_add_f32_e32 v60, v60, v76
	v_add_f32_e32 v61, v61, v77
	v_add_f32_e32 v62, v62, v78
	v_add_f32_e32 v63, v63, v79
	s_waitcnt lgkmcnt(1)
	v_add_f32_e32 v76, v28, v20
	v_add_f32_e32 v77, v29, v21
	v_add_f32_e32 v78, v30, v22
	v_add_f32_e32 v79, v31, v23
	ds_read_b128 v[20:23], v80 offset:12304
	s_lshl_b32 s2, s40, 8
	s_and_b32 s94, s2, 0x700
	s_lshl_b64 s[2:3], s[24:25], 27
	s_lshl_b64 s[28:29], s[28:29], 20
	s_waitcnt lgkmcnt(1)
	v_add_f32_e32 v81, v0, v16
	v_add_f32_e32 v82, v1, v17
	v_add_f32_e32 v83, v2, v18
	v_add_f32_e32 v84, v3, v19
	ds_read_b128 v[0:3], v80 offset:12320
	s_add_u32 s2, s38, s2
	s_addc_u32 s3, s39, s3
	s_add_u32 s2, s2, s28
	s_waitcnt lgkmcnt(1)
	v_add_f32_e32 v85, v4, v20
	v_add_f32_e32 v86, v5, v21
	v_add_f32_e32 v87, v6, v22
	v_add_f32_e32 v88, v7, v23
	ds_read_b128 v[4:7], v80 offset:12336
	s_addc_u32 s3, s3, s29
	s_lshl_b32 s25, s94, 2
	s_add_u32 s28, s2, s25
	s_waitcnt lgkmcnt(1)
	v_add_f32_e32 v80, v8, v0
	v_and_b32_e32 v0, 0x3fffff80, v197
	s_addc_u32 s29, s3, 0
	v_lshlrev_b32_e32 v0, 2, v0
	s_add_i32 s25, 0, 0x20000
	v_add3_u32 v96, s25, v0, v194
	v_add_f32_e32 v89, v9, v1
	v_add_f32_e32 v90, v10, v2
	v_add_f32_e32 v91, v11, v3
	s_waitcnt lgkmcnt(0)
	v_add_f32_e32 v92, v12, v4
	v_add_f32_e32 v93, v13, v5
	v_add_f32_e32 v94, v14, v6
	v_add_f32_e32 v95, v15, v7
	ds_read_b128 v[0:3], v96 offset:128
	ds_read_b128 v[4:7], v96
	ds_read_b128 v[8:11], v96 offset:32
	ds_read_b128 v[12:15], v96 offset:256
	ds_read_b128 v[16:19], v96 offset:384
	ds_read_b128 v[20:23], v96 offset:160
	s_waitcnt lgkmcnt(4)
	v_add_f32_e32 v0, v4, v0
	ds_read_b128 v[24:27], v96 offset:288
	ds_read_b128 v[28:31], v96 offset:416
	v_ashrrev_i32_e32 v197, 31, v196
	s_waitcnt lgkmcnt(3)
	v_add_f32_e32 v4, v12, v16
	v_add_f32_e32 v0, v0, v4
	v_rcp_f32_e32 v97, v0
	v_add_f32_e32 v0, v5, v1
	v_add_f32_e32 v1, v13, v17
	v_add_f32_e32 v0, v0, v1
	v_rcp_f32_e32 v98, v0
	v_add_f32_e32 v0, v6, v2
	v_add_f32_e32 v1, v14, v18
	v_add_f32_e32 v0, v0, v1
	v_rcp_f32_e32 v99, v0
	v_add_f32_e32 v0, v7, v3
	v_add_f32_e32 v1, v15, v19
	v_add_f32_e32 v0, v0, v1
	v_rcp_f32_e32 v100, v0
	s_waitcnt lgkmcnt(2)
	v_add_f32_e32 v0, v8, v20
	s_waitcnt lgkmcnt(0)
	v_add_f32_e32 v1, v24, v28
	v_add_f32_e32 v0, v0, v1
	v_rcp_f32_e32 v101, v0
	v_add_f32_e32 v0, v9, v21
	v_add_f32_e32 v1, v25, v29
	v_add_f32_e32 v0, v0, v1
	v_rcp_f32_e32 v102, v0
	v_add_f32_e32 v0, v10, v22
	v_add_f32_e32 v1, v26, v30
	v_add_f32_e32 v0, v0, v1
	v_rcp_f32_e32 v103, v0
	v_add_f32_e32 v0, v11, v23
	v_add_f32_e32 v1, v27, v31
	v_add_f32_e32 v0, v0, v1
	v_rcp_f32_e32 v104, v0
	ds_read_b128 v[0:3], v96 offset:64
	ds_read_b128 v[4:7], v96 offset:192
	ds_read_b128 v[8:11], v96 offset:320
	ds_read_b128 v[12:15], v96 offset:448
	ds_read_b128 v[16:19], v96 offset:96
	ds_read_b128 v[20:23], v96 offset:224
	s_waitcnt lgkmcnt(4)
	v_add_f32_e32 v0, v0, v4
	ds_read_b128 v[24:27], v96 offset:352
	ds_read_b128 v[28:31], v96 offset:480
	s_waitcnt lgkmcnt(4)
	v_add_f32_e32 v4, v8, v12
	v_add_f32_e32 v0, v0, v4
	v_rcp_f32_e32 v4, v0
	v_add_f32_e32 v0, v1, v5
	v_add_f32_e32 v1, v9, v13
	v_add_f32_e32 v0, v0, v1
	v_rcp_f32_e32 v5, v0
	v_add_f32_e32 v0, v2, v6
	v_add_f32_e32 v1, v10, v14
	v_add_f32_e32 v0, v0, v1
	v_rcp_f32_e32 v6, v0
	v_add_f32_e32 v0, v3, v7
	v_add_f32_e32 v1, v11, v15
	v_add_f32_e32 v0, v0, v1
	v_rcp_f32_e32 v7, v0
	s_waitcnt lgkmcnt(2)
	v_add_f32_e32 v0, v16, v20
	s_waitcnt lgkmcnt(0)
; __device__ __forceinline__ int crow(int r, int hi) { return (r & 3) + 8 * (r >> 2) + 4 * hi; }
; template <int MODE> ...
;     ...
;   float* Ow = Ob + (long)(g * 32) * LDO + kh * 128;
;   if (MODE == 0) {
; #pragma unroll
;     for (int r = 0; r < 16; ++r) { const int orow = crow(r, hi);
; #pragma unroll
;       for (int d0 = 0; d0 < 4; ++d0) Ow[(long)orow * LDO + d0 * 32 + r32] = o[d0][r] * rli[r]; }
;     asm volatile("s_waitcnt vmcnt(0)" ::: "memory"); __syncthreads();
	v_add_f32_e32 v1, v24, v28
	v_add_f32_e32 v0, v0, v1
	v_rcp_f32_e32 v8, v0
	v_add_f32_e32 v0, v17, v21
	v_add_f32_e32 v1, v25, v29
	v_add_f32_e32 v0, v0, v1
	v_rcp_f32_e32 v9, v0
	v_add_f32_e32 v0, v18, v22
	v_add_f32_e32 v1, v26, v30
	v_add_f32_e32 v0, v0, v1
	v_rcp_f32_e32 v10, v0
	v_add_f32_e32 v0, v19, v23
	v_add_f32_e32 v1, v27, v31
	v_add_f32_e32 v0, v0, v1
	v_rcp_f32_e32 v11, v0
	v_lshlrev_b64 v[0:1], 13, v[196:197]
	v_lshl_add_u64 v[0:1], s[28:29], 0, v[0:1]
	v_lshlrev_b32_e32 v194, 9, v211
	v_lshl_add_u64 v[0:1], v[0:1], 0, v[194:195]
	v_lshlrev_b32_e32 v194, 2, v206
	v_lshlrev_b32_e32 v2, 15, v207
	v_lshl_add_u64 v[0:1], v[0:1], 0, v[194:195]
	v_mov_b32_e32 v3, v195
	v_lshl_add_u64 v[0:1], v[0:1], 0, v[2:3]
	v_mul_f32_e32 v2, v64, v97
	global_store_dword v[0:1], v2, off
	v_mul_f32_e32 v2, v48, v97
	global_store_dword v[0:1], v2, off offset:128
	v_mul_f32_e32 v2, v32, v97
	global_store_dword v[0:1], v2, off offset:256
	v_mul_f32_e32 v2, v81, v97
	global_store_dword v[0:1], v2, off offset:384
	v_add_co_u32_e32 v2, vcc, s57, v0
	v_mul_f32_e32 v12, v65, v98
	s_nop 0
	v_addc_co_u32_e32 v3, vcc, 0, v1, vcc
	global_store_dword v[2:3], v12, off
	v_mul_f32_e32 v12, v49, v98
	global_store_dword v[2:3], v12, off offset:128
	v_mul_f32_e32 v12, v33, v98
	global_store_dword v[2:3], v12, off offset:256
	v_mul_f32_e32 v12, v82, v98
	global_store_dword v[2:3], v12, off offset:384
	v_add_co_u32_e32 v2, vcc, s62, v0
	v_mul_f32_e32 v12, v66, v99
	s_nop 0
	v_addc_co_u32_e32 v3, vcc, 0, v1, vcc
	global_store_dword v[2:3], v12, off
	v_mul_f32_e32 v12, v50, v99
	global_store_dword v[2:3], v12, off offset:128
	v_mul_f32_e32 v12, v34, v99
	global_store_dword v[2:3], v12, off offset:256
	v_mul_f32_e32 v12, v83, v99
	global_store_dword v[2:3], v12, off offset:384
	v_add_co_u32_e32 v2, vcc, s66, v0
	v_mul_f32_e32 v12, v67, v100
	s_nop 0
	v_addc_co_u32_e32 v3, vcc, 0, v1, vcc
	global_store_dword v[2:3], v12, off
	v_mul_f32_e32 v12, v51, v100
	global_store_dword v[2:3], v12, off offset:128
	v_mul_f32_e32 v12, v35, v100
	global_store_dword v[2:3], v12, off offset:256
	v_mul_f32_e32 v12, v84, v100
	global_store_dword v[2:3], v12, off offset:384
	v_add_co_u32_e32 v2, vcc, s64, v0
	v_mul_f32_e32 v12, v68, v101
	s_nop 0
	v_addc_co_u32_e32 v3, vcc, 0, v1, vcc
	global_store_dword v[2:3], v12, off
	v_mul_f32_e32 v12, v52, v101
	global_store_dword v[2:3], v12, off offset:128
	v_mul_f32_e32 v12, v36, v101
	global_store_dword v[2:3], v12, off offset:256
	v_mul_f32_e32 v12, v85, v101
	global_store_dword v[2:3], v12, off offset:384
	v_add_co_u32_e32 v2, vcc, s67, v0
	v_mul_f32_e32 v12, v69, v102
	s_nop 0
	v_addc_co_u32_e32 v3, vcc, 0, v1, vcc
	global_store_dword v[2:3], v12, off
	v_mul_f32_e32 v12, v53, v102
	global_store_dword v[2:3], v12, off offset:128
	v_mul_f32_e32 v12, v37, v102
	global_store_dword v[2:3], v12, off offset:256
	v_mul_f32_e32 v12, v86, v102
	global_store_dword v[2:3], v12, off offset:384
	v_add_co_u32_e32 v2, vcc, s68, v0
	v_mul_f32_e32 v12, v70, v103
	s_nop 0
	v_addc_co_u32_e32 v3, vcc, 0, v1, vcc
	global_store_dword v[2:3], v12, off
	v_mul_f32_e32 v12, v54, v103
	global_store_dword v[2:3], v12, off offset:128
	v_mul_f32_e32 v12, v38, v103
	global_store_dword v[2:3], v12, off offset:256
	v_mul_f32_e32 v12, v87, v103
	global_store_dword v[2:3], v12, off offset:384
	v_add_co_u32_e32 v2, vcc, s69, v0
	v_mul_f32_e32 v12, v71, v104
	s_nop 0
	v_addc_co_u32_e32 v3, vcc, 0, v1, vcc
	global_store_dword v[2:3], v12, off
	v_mul_f32_e32 v12, v55, v104
	global_store_dword v[2:3], v12, off offset:128
	v_mul_f32_e32 v12, v39, v104
	global_store_dword v[2:3], v12, off offset:256
	v_mul_f32_e32 v12, v88, v104
	global_store_dword v[2:3], v12, off offset:384
	v_add_co_u32_e32 v2, vcc, s63, v0
	v_mul_f32_e32 v12, v56, v4
	s_nop 0
	v_addc_co_u32_e32 v3, vcc, 0, v1, vcc
	global_store_dword v[2:3], v12, off
	v_mul_f32_e32 v12, v40, v4
	global_store_dword v[2:3], v12, off offset:128
	v_mul_f32_e32 v12, v72, v4
	v_mul_f32_e32 v4, v80, v4
	global_store_dword v[2:3], v12, off offset:256
	global_store_dword v[2:3], v4, off offset:384
	v_add_co_u32_e32 v2, vcc, s70, v0
	v_mul_f32_e32 v4, v57, v5
	s_nop 0
	v_addc_co_u32_e32 v3, vcc, 0, v1, vcc
	global_store_dword v[2:3], v4, off
	v_mul_f32_e32 v4, v41, v5
	global_store_dword v[2:3], v4, off offset:128
	v_mul_f32_e32 v4, v73, v5
	global_store_dword v[2:3], v4, off offset:256
	v_mul_f32_e32 v4, v89, v5
	global_store_dword v[2:3], v4, off offset:384
	v_add_co_u32_e32 v2, vcc, s71, v0
	v_mul_f32_e32 v4, v58, v6
	s_nop 0
	v_addc_co_u32_e32 v3, vcc, 0, v1, vcc
	global_store_dword v[2:3], v4, off
	v_mul_f32_e32 v4, v42, v6
	global_store_dword v[2:3], v4, off offset:128
	v_mul_f32_e32 v4, v74, v6
	global_store_dword v[2:3], v4, off offset:256
	v_mul_f32_e32 v4, v90, v6
	global_store_dword v[2:3], v4, off offset:384
	v_add_co_u32_e32 v2, vcc, s72, v0
	v_mul_f32_e32 v4, v59, v7
	s_nop 0
	v_addc_co_u32_e32 v3, vcc, 0, v1, vcc
	global_store_dword v[2:3], v4, off
	v_mul_f32_e32 v4, v43, v7
	global_store_dword v[2:3], v4, off offset:128
	v_mul_f32_e32 v4, v75, v7
	global_store_dword v[2:3], v4, off offset:256
	v_mul_f32_e32 v4, v91, v7
	global_store_dword v[2:3], v4, off offset:384
	v_add_co_u32_e32 v2, vcc, s73, v0
	v_mul_f32_e32 v4, v60, v8
	s_nop 0
	v_addc_co_u32_e32 v3, vcc, 0, v1, vcc
	global_store_dword v[2:3], v4, off
	v_mul_f32_e32 v4, v44, v8
	global_store_dword v[2:3], v4, off offset:128
	v_mul_f32_e32 v4, v76, v8
	global_store_dword v[2:3], v4, off offset:256
	v_mul_f32_e32 v4, v92, v8
	global_store_dword v[2:3], v4, off offset:384
	v_add_co_u32_e32 v2, vcc, s74, v0
	v_mul_f32_e32 v4, v61, v9
	s_nop 0
	v_addc_co_u32_e32 v3, vcc, 0, v1, vcc
	global_store_dword v[2:3], v4, off
	v_mul_f32_e32 v4, v45, v9
	global_store_dword v[2:3], v4, off offset:128
	v_mul_f32_e32 v4, v77, v9
	global_store_dword v[2:3], v4, off offset:256
	v_mul_f32_e32 v4, v93, v9
	global_store_dword v[2:3], v4, off offset:384
	v_add_co_u32_e32 v2, vcc, s75, v0
	v_mul_f32_e32 v4, v62, v10
	s_nop 0
	v_addc_co_u32_e32 v3, vcc, 0, v1, vcc
	global_store_dword v[2:3], v4, off
	v_mul_f32_e32 v4, v46, v10
	global_store_dword v[2:3], v4, off offset:128
	v_mul_f32_e32 v4, v78, v10
	global_store_dword v[2:3], v4, off offset:256
	v_mul_f32_e32 v4, v94, v10
	v_add_co_u32_e32 v0, vcc, s76, v0
	global_store_dword v[2:3], v4, off offset:384
	v_mul_f32_e32 v2, v63, v11
	v_addc_co_u32_e32 v1, vcc, 0, v1, vcc
	global_store_dword v[0:1], v2, off
	v_mul_f32_e32 v2, v47, v11
	global_store_dword v[0:1], v2, off offset:128
	v_mul_f32_e32 v2, v79, v11
	global_store_dword v[0:1], v2, off offset:256
	v_mul_f32_e32 v2, v95, v11
	global_store_dword v[0:1], v2, off offset:384
	v_mov_b32_e32 v194, v224
	s_waitcnt vmcnt(0)
	s_waitcnt vmcnt(63) expcnt(7) lgkmcnt(15)
	s_barrier
; __device__ __forceinline__ int v_rd_base(int lane) { return ((lane & 3) << 3) | (((lane >> 2) & 3) << 6) | (((lane >> 4) & 1) << 5) | (((lane >> 5) & 1) << 8); }
; #define RAWBAR() do { asm volatile("s_waitcnt lgkmcnt(0)" ::: "memory"); __builtin_amdgcn_s_barrier(); asm volatile("" ::: "memory"); } while (0)
; #define RAWBAR() do { asm volatile("s_waitcnt lgkmcnt(0)" ::: "memory"); __builtin_amdgcn_s_barrier(); asm volatile("" ::: "memory"); } while (0)
; #define RAWBAR() do { asm volatile("s_waitcnt lgkmcnt(0)" ::: "memory"); __builtin_amdgcn_s_barrier(); asm volatile("" ::: "memory"); } while (0)
; #define RAWBAR() do { asm volatile("s_waitcnt lgkmcnt(0)" ::: "memory"); __builtin_amdgcn_s_barrier(); asm volatile("" ::: "memory"); } while (0)
; #define RAWBAR() do { asm volatile("s_waitcnt lgkmcnt(0)" ::: "memory"); __builtin_amdgcn_s_barrier(); asm volatile("" ::: "memory"); } while (0)
; #define RAWBAR() do { asm volatile("s_waitcnt lgkmcnt(0)" ::: "memory"); __builtin_amdgcn_s_barrier(); asm volatile("" ::: "memory"); } while (0)
; template <int MODE> ...
;     ...
;   const bf16* Qw = Qb + (long)(g * 32 + r32) * 128 + hi * 8;
; #pragma unroll
;   for (int d0 = 0; d0 < 8; ++d0) qr[d0] = St::ld8(Qw + d0 * 16);
;   const int vb0 = (int)(uintptr_t)V_lds + v_rd_base(lane) + 2 * kh * 4096;
;   const int krow = 32 * kh + r32;
;   typedef __attribute__((address_space(3))) unsigned lds_u32;
;   const int wu = __builtin_amdgcn_readfirstlane(wid);
;   long gk[2], gv[2];
; #pragma unroll
;   for (int c = 0; c < 2; ++c) { const int q = wu + 8 * c;
;     const int r = 4 * q + (lane >> 4), pch = lane & 15; gk[c] = (long)r * 128 + ((pch ^ (r & 7)) * 8);
;     const int st = 2 * q + (lane >> 5), kk = (st >> 2) * 8 + ((lane >> 2) & 7), k = (kk & ~0xC) | ((kk & 4) << 1) | ((kk & 8) >> 1), cc = (st & 3) * 32 + (lane & 3) * 8;
;     gv[c] = (long)k * 256 + cc; }
;     ...
;   const int NT = seq / KVBLK;
;   STAGE(0, 0); asm volatile("s_waitcnt vmcnt(0)" ::: "memory"); RAWBAR();
	v_mov_b32_e32 v199, v195
	v_ashrrev_i32_e32 v217, 7, v194
	v_and_b32_e32 v214, 31, v194
	v_lshlrev_b32_e32 v196, 5, v217
	v_or_b32_e32 v0, v196, v214
	v_ashrrev_i32_e32 v1, 31, v0
	v_bfe_u32 v213, v194, 5, 1
	v_lshlrev_b64 v[0:1], 8, v[0:1]
	v_lshl_add_u64 v[0:1], s[34:35], 0, v[0:1]
	v_lshlrev_b32_e32 v198, 4, v213
	v_lshl_add_u64 v[0:1], v[0:1], 0, v[198:199]
	v_lshl_add_u64 v[2:3], v[0:1], 0, s[20:21]
	v_add_co_u32_e32 v0, vcc, s77, v0
	v_ashrrev_i32_e32 v215, 6, v194
	s_add_u32 s36, s36, 0x410000
	v_addc_co_u32_e32 v1, vcc, 0, v1, vcc
	v_readfirstlane_b32 s2, v215
	s_addc_u32 s37, s37, 0
	global_load_dwordx4 v[184:187], v[2:3], off offset:32
	global_load_dwordx4 v[180:183], v[2:3], off offset:64
	global_load_dwordx4 v[176:179], v[2:3], off offset:96
	global_load_dwordx4 v[172:175], v[2:3], off offset:128
	global_load_dwordx4 v[168:171], v[2:3], off offset:160
	global_load_dwordx4 v[164:167], v[2:3], off offset:192
	global_load_dwordx4 v[188:191], v[0:1], off
	global_load_dwordx4 v[160:163], v[2:3], off offset:224
	v_bfe_u32 v199, v194, 4, 2
	v_bfe_u32 v0, v194, 2, 2
	v_lshrrev_b32_e32 v1, 1, v194
	s_lshl_b32 s3, s2, 2
	s_lshl_b32 s34, s2, 1
	v_and_or_b32 v6, v1, 8, v0
	v_or_b32_e32 v0, s3, v199
	s_and_b32 s3, s3, -16
	s_and_b32 s35, s34, 4
	s_or_b32 s3, s3, s35
	v_or_b32_e32 v2, s3, v6
	s_add_i32 s3, s2, 8
	v_and_b32_e32 v4, 63, v194
	v_and_or_b32 v14, s34, 2, v213
	s_lshl_b32 s34, s3, 2
	s_lshl_b32 s35, s3, 1
	v_lshlrev_b32_e32 v8, 3, v4
	v_lshlrev_b32_e32 v197, 4, v4
	v_or_b32_e32 v4, s34, v199
	s_and_b32 s34, s34, -16
	s_and_b32 s41, s35, 4
	v_lshlrev_b32_e32 v9, 1, v194
	v_and_b32_e32 v211, 15, v194
	v_ashrrev_i32_e32 v1, 31, v0
	s_or_b32 s34, s34, s41
	v_and_b32_e32 v12, 0x100, v8
	v_bitop3_b32 v10, v0, v211, 7 bitop3:0x6c
	v_ashrrev_i32_e32 v5, 31, v4
	v_bitop3_b32 v15, v4, v211, 7 bitop3:0x6c
	v_or_b32_e32 v6, s34, v6
	v_and_b32_e32 v17, 24, v8
	v_and_b32_e32 v19, 32, v9
	v_lshlrev_b64 v[8:9], 8, v[0:1]
	s_lshl_b32 s34, s2, 10
	v_lshlrev_b32_e32 v212, 3, v194
	v_and_or_b32 v16, s35, 2, v213
	v_lshl_or_b32 v8, v10, 4, v8
	s_add_i32 s35, s34, 0
	v_lshlrev_b64 v[4:5], 8, v[4:5]
	v_lshlrev_b32_e32 v15, 4, v15
	v_and_b32_e32 v13, 24, v212
	v_ashrrev_i32_e32 v3, 31, v2
	v_lshl_add_u64 v[10:11], s[36:37], 0, v[8:9]
	s_mov_b32 m0, s35
	v_or_b32_e32 v4, v4, v15
	v_ashrrev_i32_e32 v7, 31, v6
	global_load_lds_dwordx4 v[10:11], off
	v_lshl_add_u64 v[128:129], v[10:11], 0, s[18:19]
	v_lshl_add_u64 v[4:5], s[36:37], 0, v[4:5]
	v_lshl_add_u64 v[130:131], v[4:5], 0, s[18:19]
	s_add_i32 m0, s35, 0x2000
	v_lshlrev_b32_e32 v1, 6, v14
	v_lshlrev_b32_e32 v10, 1, v13
	v_lshlrev_b64 v[2:3], 9, v[2:3]
	global_load_lds_dwordx4 v[4:5], off
	s_add_i32 m0, s35, 0x4000
	s_nop 0
	global_load_lds_dwordx4 v[128:129], off
	s_add_i32 m0, s35, 0x6000
	s_nop 0
	global_load_lds_dwordx4 v[130:131], off
	v_or3_b32 v4, v1, v10, v2
	v_lshrrev_b32_e32 v132, 11, v4
	v_lshrrev_b32_e32 v133, 12, v4
	v_xor_b32_e32 v132, v132, v133
	v_and_b32_e32 v132, 1, v132
	v_mul_u32_u24_e32 v132, 0x1800, v132
	v_xor_b32_e32 v4, v4, v132
	v_mov_b32_e32 v5, v3
	v_lshlrev_b32_e32 v1, 6, v16
	v_lshlrev_b64 v[6:7], 9, v[6:7]
	v_lshl_add_u64 v[4:5], s[30:31], 0, v[4:5]
	s_add_i32 m0, s35, 0x8000
	v_or3_b32 v10, v1, v10, v6
	v_lshrrev_b32_e32 v132, 11, v10
	v_lshrrev_b32_e32 v133, 12, v10
	v_xor_b32_e32 v132, v132, v133
	v_and_b32_e32 v132, 1, v132
	v_mul_u32_u24_e32 v132, 0x1800, v132
	v_xor_b32_e32 v10, v10, v132
	v_mov_b32_e32 v11, v7
	global_load_lds_dwordx4 v[4:5], off
	v_lshl_add_u64 v[10:11], s[30:31], 0, v[10:11]
	s_add_i32 m0, s35, 0xa000
	v_lshl_add_u64 v[4:5], v[4:5], 0, s[10:11]
	global_load_lds_dwordx4 v[10:11], off
	s_add_i32 m0, s35, 0xc000
	v_and_b32_e32 v216, 1, v215
	global_load_lds_dwordx4 v[4:5], off
	v_lshl_add_u64 v[4:5], v[10:11], 0, s[10:11]
	s_add_i32 m0, s35, 0xe000
	v_lshlrev_b32_e32 v20, 13, v216
	global_load_lds_dwordx4 v[4:5], off
	s_cmp_lg_u32 s33, -1
	v_lshl_or_b32 v1, v214, 8, v20
	s_cselect_b32 s30, s33, 0
	s_and_b32 s2, s2, 1
	v_lshlrev_b32_e32 v4, 4, v194
	v_add_u32_e32 v220, 0, v1
	s_lshl_b32 s2, s2, 6
	v_and_b32_e32 v1, 32, v194
	v_and_b32_e32 v5, 0x70, v4
	v_bitop3_b32 v229, v198, v4, s58 bitop3:0x78
	v_or3_b32 v4, s2, v1, v13
	s_and_b32 s2, s3, 1
	s_lshl_b32 s2, s2, 6
	v_or3_b32 v1, s2, v1, v13
	v_add_u32_e32 v0, 32, v0
	v_and_b32_e32 v18, 0xc0, v197
	s_waitcnt vmcnt(0)
	v_lshl_or_b32 v6, v1, 1, v6
	v_ashrrev_i32_e32 v1, 31, v0
	s_waitcnt lgkmcnt(0)
	s_barrier
; __device__ __forceinline__ int v_rd_base(int lane) { return ((lane & 3) << 3) | (((lane >> 2) & 3) << 6) | (((lane >> 4) & 1) << 5) | (((lane >> 5) & 1) << 8); }
; #define RAWBAR() do { asm volatile("s_waitcnt lgkmcnt(0)" ::: "memory"); __builtin_amdgcn_s_barrier(); asm volatile("" ::: "memory"); } while (0)
; #define RAWBAR() do { asm volatile("s_waitcnt lgkmcnt(0)" ::: "memory"); __builtin_amdgcn_s_barrier(); asm volatile("" ::: "memory"); } while (0)
; #define RAWBAR() do { asm volatile("s_waitcnt lgkmcnt(0)" ::: "memory"); __builtin_amdgcn_s_barrier(); asm volatile("" ::: "memory"); } while (0)
; template <int MODE> ...
;     ...
;   f32x16 o[8] = {}; bf16x8 qr[8]; float lsum = 0.f;
;   const bf16* Qw = Qb + (long)(g * 32 + r32) * 128 + hi * 8;
; #pragma unroll
;   for (int d0 = 0; d0 < 8; ++d0) qr[d0] = St::ld8(Qw + d0 * 16);
;   const int vb0 = (int)(uintptr_t)V_lds + v_rd_base(lane) + 2 * kh * 4096;
;   const int krow = 32 * kh + r32;
;   typedef __attribute__((address_space(3))) unsigned lds_u32;
;   const int wu = __builtin_amdgcn_readfirstlane(wid);
;   long gk[2], gv[2];
; #pragma unroll
;   for (int c = 0; c < 2; ++c) { const int q = wu + 8 * c;
;     const int r = 4 * q + (lane >> 4), pch = lane & 15; gk[c] = (long)r * 128 + ((pch ^ (r & 7)) * 8);
;     const int st = 2 * q + (lane >> 5), kk = (st >> 2) * 8 + ((lane >> 2) & 7), k = (kk & ~0xC) | ((kk & 4) << 1) | ((kk & 8) >> 1), cc = (st & 3) * 32 + (lane & 3) * 8;
;     gv[c] = (long)k * 256 + cc; }
;     ...
;   const int NT = seq / KVBLK;
;   STAGE(0, 0); asm volatile("s_waitcnt vmcnt(0)" ::: "memory"); RAWBAR();
;   if (false) __builtin_amdgcn_s_setprio(1);
;   for (int j = 0; j < NT; ++j) {
;     const int buf = j & 1;
;     if (j + 1 < NT) { STAGE((j + 1) * KVBLK, buf ^ 1); }
;     const char* Kb = K_lds + buf * 16384;
;     f32x16 pe = {}, po = {};
; #pragma unroll
;     for (int d0 = 0; d0 < 8; d0 += 2) {
;       const bf16x8 k0 = *reinterpret_cast<const bf16x8*>(Kb + KSWZ(krow, (d0 * 16 + hi * 8) * 2));
;       const bf16x8 k1 = *reinterpret_cast<const bf16x8*>(Kb + KSWZ(krow, ((d0 + 1) * 16 + hi * 8) * 2));
;       pe = __builtin_amdgcn_mfma_f32_32x32x16_bf16(k0, qr[d0], pe, 0, 0, 0);
;       po = __builtin_amdgcn_mfma_f32_32x32x16_bf16(k1, qr[d0 + 1], po, 0, 0, 0); }
	v_add_u32_e32 v10, s30, v18
	v_readlane_b32 s84, v251, 28
	v_lshlrev_b64 v[0:1], 8, v[0:1]
	v_add3_u32 v10, v10, v17, v19
	v_lshl_or_b32 v2, v4, 1, v2
	v_readlane_b32 s85, v251, 29
	v_or_b32_e32 v0, v0, v15
	v_mov_b32_e32 v219, 0
	s_mov_b32 s40, 0
	v_add3_u32 v218, v10, v12, v20
	v_bitop3_b32 v228, v198, v5, 32 bitop3:0x36
	v_bitop3_b32 v227, v198, v5, 64 bitop3:0x36
	v_bitop3_b32 v226, v198, v5, s43 bitop3:0x36
	v_bitop3_b32 v225, v198, v5, s59 bitop3:0x36
	v_bitop3_b32 v223, v198, v5, s60 bitop3:0x36
	v_bitop3_b32 v222, v198, v5, s56 bitop3:0x36
	v_bitop3_b32 v221, v198, v5, s61 bitop3:0x36
	v_lshl_add_u64 v[200:201], s[84:85], 0, v[2:3]
	v_lshl_add_u64 v[202:203], s[84:85], 0, v[6:7]
	v_lshl_add_u64 v[204:205], s[8:9], 0, v[8:9]
	v_lshl_add_u64 v[206:207], s[8:9], 0, v[0:1]
	v_mov_b32_e32 v0, 0
	v_mov_b32_e32 v1, v219
	v_mov_b32_e32 v2, v219
	v_mov_b32_e32 v3, v219
	v_mov_b32_e32 v4, v219
	v_mov_b32_e32 v5, v219
	v_mov_b32_e32 v6, v219
	v_mov_b32_e32 v7, v219
	v_mov_b32_e32 v8, v219
	v_mov_b32_e32 v9, v219
	v_mov_b32_e32 v10, v219
	v_mov_b32_e32 v11, v219
	v_mov_b32_e32 v12, v219
	v_mov_b32_e32 v13, v219
	v_mov_b32_e32 v14, v219
	v_mov_b32_e32 v15, v219
	v_mov_b32_e32 v48, 0
	v_mov_b32_e32 v49, v219
	v_mov_b32_e32 v50, v219
	v_mov_b32_e32 v51, v219
	v_mov_b32_e32 v52, v219
	v_mov_b32_e32 v53, v219
	v_mov_b32_e32 v54, v219
	v_mov_b32_e32 v55, v219
	v_mov_b32_e32 v56, v219
	v_mov_b32_e32 v57, v219
	v_mov_b32_e32 v58, v219
	v_mov_b32_e32 v59, v219
	v_mov_b32_e32 v60, v219
	v_mov_b32_e32 v61, v219
	v_mov_b32_e32 v62, v219
	v_mov_b32_e32 v63, v219
	v_mov_b32_e32 v16, 0
	v_mov_b32_e32 v17, v219
	v_mov_b32_e32 v18, v219
	v_mov_b32_e32 v19, v219
	v_mov_b32_e32 v20, v219
	v_mov_b32_e32 v21, v219
	v_mov_b32_e32 v22, v219
	v_mov_b32_e32 v23, v219
	v_mov_b32_e32 v24, v219
	v_mov_b32_e32 v25, v219
	v_mov_b32_e32 v26, v219
	v_mov_b32_e32 v27, v219
	v_mov_b32_e32 v28, v219
	v_mov_b32_e32 v29, v219
	v_mov_b32_e32 v30, v219
	v_mov_b32_e32 v31, v219
	v_mov_b32_e32 v32, 0
	v_mov_b32_e32 v33, v219
	v_mov_b32_e32 v34, v219
	v_mov_b32_e32 v35, v219
	v_mov_b32_e32 v36, v219
	v_mov_b32_e32 v37, v219
	v_mov_b32_e32 v38, v219
	v_mov_b32_e32 v39, v219
	v_mov_b32_e32 v40, v219
	v_mov_b32_e32 v41, v219
	v_mov_b32_e32 v42, v219
	v_mov_b32_e32 v43, v219
	v_mov_b32_e32 v44, v219
	v_mov_b32_e32 v45, v219
	v_mov_b32_e32 v46, v219
	v_mov_b32_e32 v47, v219
	v_mov_b32_e32 v64, 0
	v_mov_b32_e32 v65, v219
	v_mov_b32_e32 v66, v219
	v_mov_b32_e32 v67, v219
	v_mov_b32_e32 v68, v219
	v_mov_b32_e32 v69, v219
	v_mov_b32_e32 v70, v219
	v_mov_b32_e32 v71, v219
	v_mov_b32_e32 v72, v219
	v_mov_b32_e32 v73, v219
	v_mov_b32_e32 v74, v219
	v_mov_b32_e32 v75, v219
	v_mov_b32_e32 v76, v219
	v_mov_b32_e32 v77, v219
	v_mov_b32_e32 v78, v219
	v_mov_b32_e32 v79, v219
	v_mov_b32_e32 v80, 0
	v_mov_b32_e32 v81, v219
	v_mov_b32_e32 v82, v219
	v_mov_b32_e32 v83, v219
	v_mov_b32_e32 v84, v219
	v_mov_b32_e32 v85, v219
	v_mov_b32_e32 v86, v219
	v_mov_b32_e32 v87, v219
	v_mov_b32_e32 v88, v219
	v_mov_b32_e32 v89, v219
	v_mov_b32_e32 v90, v219
	v_mov_b32_e32 v91, v219
	v_mov_b32_e32 v92, v219
	v_mov_b32_e32 v93, v219
	v_mov_b32_e32 v94, v219
	v_mov_b32_e32 v95, v219
	v_mov_b32_e32 v96, 0
	v_mov_b32_e32 v97, v219
	v_mov_b32_e32 v98, v219
	v_mov_b32_e32 v99, v219
	v_mov_b32_e32 v100, v219
	v_mov_b32_e32 v101, v219
	v_mov_b32_e32 v102, v219
	v_mov_b32_e32 v103, v219
	v_mov_b32_e32 v104, v219
	v_mov_b32_e32 v105, v219
	v_mov_b32_e32 v106, v219
	v_mov_b32_e32 v107, v219
	v_mov_b32_e32 v108, v219
	v_mov_b32_e32 v109, v219
	v_mov_b32_e32 v110, v219
	v_mov_b32_e32 v111, v219
	v_mov_b32_e32 v112, 0
	v_mov_b32_e32 v113, v219
	v_mov_b32_e32 v114, v219
	v_mov_b32_e32 v115, v219
	v_mov_b32_e32 v116, v219
	v_mov_b32_e32 v117, v219
	v_mov_b32_e32 v118, v219
	v_mov_b32_e32 v119, v219
	v_mov_b32_e32 v120, v219
	v_mov_b32_e32 v121, v219
	v_mov_b32_e32 v122, v219
	v_mov_b32_e32 v123, v219
	v_mov_b32_e32 v124, v219
	v_mov_b32_e32 v125, v219
	v_mov_b32_e32 v126, v219
	v_mov_b32_e32 v127, v219
	v_readlane_b32 s86, v251, 30
	v_readlane_b32 s87, v251, 31
	s_waitcnt vmcnt(0)
	v_subrev_u32_e32 v225, s8, v204
	v_subrev_u32_e32 v223, s8, v206
	v_subrev_u32_e32 v222, s84, v200
	v_subrev_u32_e32 v221, s84, v202
	v_lshrrev_b32_e32 v246, 11, v222
	v_lshrrev_b32_e32 v247, 12, v222
	v_xor_b32_e32 v246, v246, v247
	v_and_b32_e32 v246, 1, v246
	v_mul_u32_u24_e32 v246, 0x1800, v246
	v_xor_b32_e32 v222, v222, v246
	v_lshrrev_b32_e32 v246, 11, v221
	v_lshrrev_b32_e32 v247, 12, v221
	v_xor_b32_e32 v246, v246, v247
	v_and_b32_e32 v246, 1, v246
	v_mul_u32_u24_e32 v246, 0x1800, v246
	v_xor_b32_e32 v221, v221, v246
	v_add_u32_e32 v246, 0x100, v222
	v_add_u32_e32 v247, 0x100, v221
	s_add_u32 s86, s8, s26
	s_addc_u32 s87, s9, s27
	s_add_u32 s86, s86, 0x4000
	s_addc_u32 s87, s87, 0
	s_add_u32 s2, s84, s26
	s_addc_u32 s3, s85, s27
	s_add_u32 s2, s2, s12
	s_addc_u32 s3, s3, s13
	v_add_u32_e32 v229, v220, v229
	v_add_u32_e32 v228, v220, v228
	v_add_u32_e32 v227, v220, v227
	v_add_u32_e32 v226, v220, v226
	ds_read_b128 v[230:233], v229 offset:0
	ds_read_b128 v[234:237], v228 offset:0
	s_waitcnt lgkmcnt(0)
	v_mfma_f32_32x32x16_bf16 v[144:159], v[230:233], v[188:191], 0
	v_mfma_f32_32x32x16_bf16 v[144:159], v[234:237], v[184:187], v[144:159]
	ds_read_b128 v[230:233], v227 offset:0
	ds_read_b128 v[234:237], v226 offset:0
	s_waitcnt lgkmcnt(0)
	v_mfma_f32_32x32x16_bf16 v[144:159], v[230:233], v[180:183], v[144:159]
	v_mfma_f32_32x32x16_bf16 v[144:159], v[234:237], v[176:179], v[144:159]
	ds_read_b128 v[230:233], v229 offset:128
	ds_read_b128 v[234:237], v228 offset:128
	s_waitcnt lgkmcnt(0)
	v_mfma_f32_32x32x16_bf16 v[144:159], v[230:233], v[172:175], v[144:159]
	v_mfma_f32_32x32x16_bf16 v[144:159], v[234:237], v[168:171], v[144:159]
	ds_read_b128 v[230:233], v227 offset:128
	ds_read_b128 v[234:237], v226 offset:128
	s_waitcnt lgkmcnt(0)
	v_mfma_f32_32x32x16_bf16 v[144:159], v[230:233], v[164:167], v[144:159]
	v_mfma_f32_32x32x16_bf16 v[144:159], v[234:237], v[160:163], v[144:159]
	s_mov_b32 s84, 0
	s_barrier
	s_cmp_lt_u32 s34, 0x1000
	s_cbranch_scc0 .LattnBpre_m1
; #define SBAR() __builtin_amdgcn_sched_barrier(0)
; #define PVR(S, DA, DB, vbase) do { S[0] = tr_read<v_rd_off(DA, 0, 0)>(vbase); S[1] = tr_read<v_rd_off(DA, 0, 1)>(vbase); S[2] = tr_read<v_rd_off(DB, 0, 0)>(vbase); S[3] = tr_read<v_rd_off(DB, 0, 1)>(vbase); \
;     S[4] = tr_read<v_rd_off(DA, 1, 0)>(vbase); S[5] = tr_read<v_rd_off(DA, 1, 1)>(vbase); S[6] = tr_read<v_rd_off(DB, 1, 0)>(vbase); S[7] = tr_read<v_rd_off(DB, 1, 1)>(vbase); } while (0)
; #define RAWBAR() do { asm volatile("s_waitcnt lgkmcnt(0)" ::: "memory"); __builtin_amdgcn_s_barrier(); asm volatile("" ::: "memory"); } while (0)
; #define RAWBAR() do { asm volatile("s_waitcnt lgkmcnt(0)" ::: "memory"); __builtin_amdgcn_s_barrier(); asm volatile("" ::: "memory"); } while (0)
; #define RAWBAR() do { asm volatile("s_waitcnt lgkmcnt(0)" ::: "memory"); __builtin_amdgcn_s_barrier(); asm volatile("" ::: "memory"); } while (0)
; #define RAWBAR() do { asm volatile("s_waitcnt lgkmcnt(0)" ::: "memory"); __builtin_amdgcn_s_barrier(); asm volatile("" ::: "memory"); } while (0)
; #define RAWBAR() do { asm volatile("s_waitcnt lgkmcnt(0)" ::: "memory"); __builtin_amdgcn_s_barrier(); asm volatile("" ::: "memory"); } while (0)
; template <int MODE> ...
;     ...
;   for (int j = 0; j < NT; ++j) {
;     const int buf = j & 1;
;     if (j + 1 < NT) { STAGE((j + 1) * KVBLK, buf ^ 1); }
;     const char* Kb = K_lds + buf * 16384;
;     f32x16 pe = {}, po = {};
; #pragma unroll
;     for (int d0 = 0; d0 < 8; d0 += 2) {
;       const bf16x8 k0 = *reinterpret_cast<const bf16x8*>(Kb + KSWZ(krow, (d0 * 16 + hi * 8) * 2));
;       const bf16x8 k1 = *reinterpret_cast<const bf16x8*>(Kb + KSWZ(krow, ((d0 + 1) * 16 + hi * 8) * 2));
;       pe = __builtin_amdgcn_mfma_f32_32x32x16_bf16(k0, qr[d0], pe, 0, 0, 0);
;       po = __builtin_amdgcn_mfma_f32_32x32x16_bf16(k1, qr[d0 + 1], po, 0, 0, 0); }
;     const int vo = vb0 + buf * 32768;
;     s16x4 R0_[8], R1_[8];
;     PVR(R0_, 0, 1, vo);
;     f32x16 p;
; #pragma unroll
;     for (int r = 0; r < 16; ++r) p[r] = __builtin_amdgcn_exp2f(fmaf(pe[r] + po[r], C, negMc));
;     float ps = 0.f;
; #pragma unroll
;     for (int r = 0; r < 16; ++r) ps += p[r];
;     lsum += ps;
;     const bf16x8 own0 = pk8(p, 0), own1 = pk8(p, 8);
;     SBAR();
;     PV_TAIL4(o, vo, vo + 16384, own0, own1);
;     asm volatile("s_waitcnt vmcnt(0)" ::: "memory");
;     RAWBAR();
.LBB0_1023:
	ds_read_b128 v[230:233], v229 offset:16384
	ds_read_b128 v[234:237], v228 offset:16384
	ds_read_b128 v[238:241], v227 offset:16384
	ds_read_b128 v[242:245], v226 offset:16384
	s_mov_b32 m0, s34
	s_nop 0
	global_load_lds_dwordx4 v225, s[86:87]
	s_add_i32 m0, s34, 0x2000
	s_nop 0
	global_load_lds_dwordx4 v223, s[86:87]
	v_exp_f32_e32 v144, v144
	v_exp_f32_e32 v145, v145
	v_exp_f32_e32 v146, v146
	v_exp_f32_e32 v147, v147
	s_waitcnt lgkmcnt(2)
	v_mfma_f32_32x32x16_bf16 v[128:143], v[230:233], v[188:191], 0
	v_mfma_f32_32x32x16_bf16 v[128:143], v[234:237], v[184:187], v[128:143]
	ds_read_b128 v[230:233], v229 offset:16512
	ds_read_b128 v[234:237], v228 offset:16512
	v_exp_f32_e32 v148, v148
	v_exp_f32_e32 v149, v149
	v_exp_f32_e32 v150, v150
	v_exp_f32_e32 v151, v151
	v_add_f32_e32 v250, v144, v145
	v_add_f32_e32 v250, v146, v250
	v_add_f32_e32 v250, v147, v250
	s_waitcnt lgkmcnt(2)
	v_mfma_f32_32x32x16_bf16 v[128:143], v[238:241], v[180:183], v[128:143]
	v_mfma_f32_32x32x16_bf16 v[128:143], v[242:245], v[176:179], v[128:143]
	ds_read_b128 v[238:241], v227 offset:16512
	ds_read_b128 v[242:245], v226 offset:16512
	v_exp_f32_e32 v152, v152
	v_exp_f32_e32 v153, v153
	v_exp_f32_e32 v154, v154
	v_exp_f32_e32 v155, v155
	v_add_f32_e32 v250, v148, v250
	v_add_f32_e32 v250, v149, v250
	v_add_f32_e32 v250, v150, v250
	v_add_f32_e32 v250, v151, v250
	s_waitcnt lgkmcnt(2)
	v_mfma_f32_32x32x16_bf16 v[128:143], v[230:233], v[172:175], v[128:143]
	v_mfma_f32_32x32x16_bf16 v[128:143], v[234:237], v[168:171], v[128:143]
	v_exp_f32_e32 v156, v156
	v_exp_f32_e32 v157, v157
	v_exp_f32_e32 v158, v158
	v_exp_f32_e32 v159, v159
	v_add_f32_e32 v250, v152, v250
	v_add_f32_e32 v250, v153, v250
	v_add_f32_e32 v250, v154, v250
	v_add_f32_e32 v250, v155, v250
	v_cvt_pk_bf16_f32 v230, v144, v145
	v_cvt_pk_bf16_f32 v231, v146, v147
	v_cvt_pk_bf16_f32 v232, v148, v149
	v_cvt_pk_bf16_f32 v233, v150, v151
	s_waitcnt lgkmcnt(0)
	v_mfma_f32_32x32x16_bf16 v[128:143], v[238:241], v[164:167], v[128:143]
	v_mfma_f32_32x32x16_bf16 v[128:143], v[242:245], v[160:163], v[128:143]
	v_add_u32_e32 v249, s84, v218
	s_add_i32 s85, s84, 0x8000
	s_cmp_eq_u32 s85, 0x18000
	s_cselect_b32 s85, 0, s85
	ds_read_b64_tr_b16 v[238:239], v249 offset:0
	ds_read_b64_tr_b16 v[240:241], v249 offset:2048
	ds_read_b64_tr_b16 v[242:243], v249 offset:512
	ds_read_b64_tr_b16 v[244:245], v249 offset:2560
	ds_read_b64_tr_b16 v[144:145], v249 offset:4096
	ds_read_b64_tr_b16 v[146:147], v249 offset:6144
	ds_read_b64_tr_b16 v[148:149], v249 offset:4608
	ds_read_b64_tr_b16 v[150:151], v249 offset:6656
	v_add_f32_e32 v250, v156, v250
	v_add_f32_e32 v250, v157, v250
	v_add_f32_e32 v250, v158, v250
	v_add_f32_e32 v250, v159, v250
	v_cvt_pk_bf16_f32 v234, v152, v153
	v_cvt_pk_bf16_f32 v235, v154, v155
	v_cvt_pk_bf16_f32 v236, v156, v157
	v_cvt_pk_bf16_f32 v237, v158, v159
	v_add_f32_e32 v219, v219, v250
	ds_read_b64_tr_b16 v[152:153], v249 offset:1024
	ds_read_b64_tr_b16 v[154:155], v249 offset:3072
	ds_read_b64_tr_b16 v[156:157], v249 offset:1536
	ds_read_b64_tr_b16 v[158:159], v249 offset:3584
	s_waitcnt lgkmcnt(8)
	v_mfma_f32_32x32x16_bf16 v[112:127], v[230:233], v[238:241], v[112:127]
	v_mfma_f32_32x32x16_bf16 v[96:111], v[230:233], v[242:245], v[96:111]
	ds_read_b64_tr_b16 v[238:239], v249 offset:5120
	ds_read_b64_tr_b16 v[240:241], v249 offset:7168
	ds_read_b64_tr_b16 v[242:243], v249 offset:5632
	ds_read_b64_tr_b16 v[244:245], v249 offset:7680
	s_add_i32 s30, s85, s34
	s_add_i32 m0, s30, 0x8000
	s_nop 0
	global_load_lds_dwordx4 v222, s[2:3]
	s_waitcnt lgkmcnt(8)
	v_mfma_f32_32x32x16_bf16 v[112:127], v[234:237], v[144:147], v[112:127]
	v_mfma_f32_32x32x16_bf16 v[96:111], v[234:237], v[148:151], v[96:111]
	ds_read_b64_tr_b16 v[144:145], v249 offset:16384
	ds_read_b64_tr_b16 v[146:147], v249 offset:18432
	ds_read_b64_tr_b16 v[148:149], v249 offset:16896
	ds_read_b64_tr_b16 v[150:151], v249 offset:18944
	s_add_i32 s30, s85, s34
	s_add_i32 m0, s30, 0xa000
	s_nop 0
	global_load_lds_dwordx4 v221, s[2:3]
	s_waitcnt lgkmcnt(8)
	v_mfma_f32_32x32x16_bf16 v[80:95], v[230:233], v[152:155], v[80:95]
	v_mfma_f32_32x32x16_bf16 v[64:79], v[230:233], v[156:159], v[64:79]
	ds_read_b64_tr_b16 v[152:153], v249 offset:20480
	ds_read_b64_tr_b16 v[154:155], v249 offset:22528
	ds_read_b64_tr_b16 v[156:157], v249 offset:20992
	ds_read_b64_tr_b16 v[158:159], v249 offset:23040
	s_add_i32 s30, s85, s34
	s_add_i32 m0, s30, 0xc000
	s_nop 0
	global_load_lds_dwordx4 v246, s[2:3]
	s_waitcnt lgkmcnt(8)
	v_mfma_f32_32x32x16_bf16 v[80:95], v[234:237], v[238:241], v[80:95]
	v_mfma_f32_32x32x16_bf16 v[64:79], v[234:237], v[242:245], v[64:79]
	ds_read_b64_tr_b16 v[238:239], v249 offset:17408
	ds_read_b64_tr_b16 v[240:241], v249 offset:19456
	ds_read_b64_tr_b16 v[242:243], v249 offset:17920
	ds_read_b64_tr_b16 v[244:245], v249 offset:19968
	s_add_i32 s30, s85, s34
	s_add_i32 m0, s30, 0xe000
	s_nop 0
	global_load_lds_dwordx4 v247, s[2:3]
	s_waitcnt lgkmcnt(8)
	v_mfma_f32_32x32x16_bf16 v[32:47], v[230:233], v[144:147], v[32:47]
	v_mfma_f32_32x32x16_bf16 v[16:31], v[230:233], v[148:151], v[16:31]
	ds_read_b64_tr_b16 v[144:145], v249 offset:21504
	ds_read_b64_tr_b16 v[146:147], v249 offset:23552
	ds_read_b64_tr_b16 v[148:149], v249 offset:22016
	ds_read_b64_tr_b16 v[150:151], v249 offset:24064
	s_waitcnt lgkmcnt(8)
	v_mfma_f32_32x32x16_bf16 v[32:47], v[234:237], v[152:155], v[32:47]
	v_mfma_f32_32x32x16_bf16 v[16:31], v[234:237], v[156:159], v[16:31]
	s_waitcnt lgkmcnt(0)
	v_mfma_f32_32x32x16_bf16 v[48:63], v[230:233], v[238:241], v[48:63]
	s_waitcnt vmcnt(0)
	s_barrier
; #define SBAR() __builtin_amdgcn_sched_barrier(0)
; #define PVR(S, DA, DB, vbase) do { S[0] = tr_read<v_rd_off(DA, 0, 0)>(vbase); S[1] = tr_read<v_rd_off(DA, 0, 1)>(vbase); S[2] = tr_read<v_rd_off(DB, 0, 0)>(vbase); S[3] = tr_read<v_rd_off(DB, 0, 1)>(vbase); \
;     S[4] = tr_read<v_rd_off(DA, 1, 0)>(vbase); S[5] = tr_read<v_rd_off(DA, 1, 1)>(vbase); S[6] = tr_read<v_rd_off(DB, 1, 0)>(vbase); S[7] = tr_read<v_rd_off(DB, 1, 1)>(vbase); } while (0)
; #define RAWBAR() do { asm volatile("s_waitcnt lgkmcnt(0)" ::: "memory"); __builtin_amdgcn_s_barrier(); asm volatile("" ::: "memory"); } while (0)
; #define RAWBAR() do { asm volatile("s_waitcnt lgkmcnt(0)" ::: "memory"); __builtin_amdgcn_s_barrier(); asm volatile("" ::: "memory"); } while (0)
; #define RAWBAR() do { asm volatile("s_waitcnt lgkmcnt(0)" ::: "memory"); __builtin_amdgcn_s_barrier(); asm volatile("" ::: "memory"); } while (0)
; #define RAWBAR() do { asm volatile("s_waitcnt lgkmcnt(0)" ::: "memory"); __builtin_amdgcn_s_barrier(); asm volatile("" ::: "memory"); } while (0)
; #define RAWBAR() do { asm volatile("s_waitcnt lgkmcnt(0)" ::: "memory"); __builtin_amdgcn_s_barrier(); asm volatile("" ::: "memory"); } while (0)
; template <int MODE> ...
;     ...
;   for (int j = 0; j < NT; ++j) {
;     const int buf = j & 1;
;     if (j + 1 < NT) { STAGE((j + 1) * KVBLK, buf ^ 1); }
;     const char* Kb = K_lds + buf * 16384;
;     f32x16 pe = {}, po = {};
; #pragma unroll
;     for (int d0 = 0; d0 < 8; d0 += 2) {
;       const bf16x8 k0 = *reinterpret_cast<const bf16x8*>(Kb + KSWZ(krow, (d0 * 16 + hi * 8) * 2));
;       const bf16x8 k1 = *reinterpret_cast<const bf16x8*>(Kb + KSWZ(krow, ((d0 + 1) * 16 + hi * 8) * 2));
;       pe = __builtin_amdgcn_mfma_f32_32x32x16_bf16(k0, qr[d0], pe, 0, 0, 0);
;       po = __builtin_amdgcn_mfma_f32_32x32x16_bf16(k1, qr[d0 + 1], po, 0, 0, 0); }
;     const int vo = vb0 + buf * 32768;
;     s16x4 R0_[8], R1_[8];
;     PVR(R0_, 0, 1, vo);
;     f32x16 p;
; #pragma unroll
;     for (int r = 0; r < 16; ++r) p[r] = __builtin_amdgcn_exp2f(fmaf(pe[r] + po[r], C, negMc));
;     float ps = 0.f;
; #pragma unroll
;     for (int r = 0; r < 16; ++r) ps += p[r];
;     lsum += ps;
;     const bf16x8 own0 = pk8(p, 0), own1 = pk8(p, 8);
;     SBAR();
;     PV_TAIL4(o, vo, vo + 16384, own0, own1);
;     asm volatile("s_waitcnt vmcnt(0)" ::: "memory");
;     RAWBAR();
	s_add_u32 s86, s86, 0x4000
	s_addc_u32 s87, s87, 0
	s_add_u32 s2, s2, 0x8000
	s_addc_u32 s3, s3, 0
	v_mfma_f32_32x32x16_bf16 v[0:15], v[230:233], v[242:245], v[0:15]
	v_mfma_f32_32x32x16_bf16 v[48:63], v[234:237], v[144:147], v[48:63]
	v_mfma_f32_32x32x16_bf16 v[0:15], v[234:237], v[148:151], v[0:15]
	s_add_i32 s84, s84, 0x8000
	s_cmp_eq_u32 s84, 0x18000
	s_cselect_b32 s84, 0, s84
	ds_read_b128 v[230:233], v229 offset:0
	ds_read_b128 v[234:237], v228 offset:0
	ds_read_b128 v[238:241], v227 offset:0
	ds_read_b128 v[242:245], v226 offset:0
	s_add_i32 m0, s34, 0x4000
	s_nop 0
	global_load_lds_dwordx4 v225, s[86:87]
	s_add_i32 m0, s34, 0x6000
	s_nop 0
	global_load_lds_dwordx4 v223, s[86:87]
	v_exp_f32_e32 v128, v128
	v_exp_f32_e32 v129, v129
	v_exp_f32_e32 v130, v130
	v_exp_f32_e32 v131, v131
	s_waitcnt lgkmcnt(2)
	v_mfma_f32_32x32x16_bf16 v[144:159], v[230:233], v[188:191], 0
	v_mfma_f32_32x32x16_bf16 v[144:159], v[234:237], v[184:187], v[144:159]
	ds_read_b128 v[230:233], v229 offset:128
	ds_read_b128 v[234:237], v228 offset:128
	v_exp_f32_e32 v132, v132
	v_exp_f32_e32 v133, v133
	v_exp_f32_e32 v134, v134
	v_exp_f32_e32 v135, v135
	v_add_f32_e32 v250, v128, v129
	v_add_f32_e32 v250, v130, v250
	v_add_f32_e32 v250, v131, v250
	s_waitcnt lgkmcnt(2)
	v_mfma_f32_32x32x16_bf16 v[144:159], v[238:241], v[180:183], v[144:159]
	v_mfma_f32_32x32x16_bf16 v[144:159], v[242:245], v[176:179], v[144:159]
	ds_read_b128 v[238:241], v227 offset:128
	ds_read_b128 v[242:245], v226 offset:128
	v_exp_f32_e32 v136, v136
	v_exp_f32_e32 v137, v137
	v_exp_f32_e32 v138, v138
	v_exp_f32_e32 v139, v139
	v_add_f32_e32 v250, v132, v250
	v_add_f32_e32 v250, v133, v250
	v_add_f32_e32 v250, v134, v250
	v_add_f32_e32 v250, v135, v250
	s_waitcnt lgkmcnt(2)
	v_mfma_f32_32x32x16_bf16 v[144:159], v[230:233], v[172:175], v[144:159]
	v_mfma_f32_32x32x16_bf16 v[144:159], v[234:237], v[168:171], v[144:159]
	v_exp_f32_e32 v140, v140
	v_exp_f32_e32 v141, v141
	v_exp_f32_e32 v142, v142
	v_exp_f32_e32 v143, v143
	v_add_f32_e32 v250, v136, v250
	v_add_f32_e32 v250, v137, v250
	v_add_f32_e32 v250, v138, v250
	v_add_f32_e32 v250, v139, v250
	v_cvt_pk_bf16_f32 v230, v128, v129
	v_cvt_pk_bf16_f32 v231, v130, v131
	v_cvt_pk_bf16_f32 v232, v132, v133
	v_cvt_pk_bf16_f32 v233, v134, v135
	s_waitcnt lgkmcnt(0)
	v_mfma_f32_32x32x16_bf16 v[144:159], v[238:241], v[164:167], v[144:159]
	v_mfma_f32_32x32x16_bf16 v[144:159], v[242:245], v[160:163], v[144:159]
	v_add_u32_e32 v249, s84, v218
	s_add_i32 s85, s84, 0x8000
	s_cmp_eq_u32 s85, 0x18000
	s_cselect_b32 s85, 0, s85
	ds_read_b64_tr_b16 v[238:239], v249 offset:0
	ds_read_b64_tr_b16 v[240:241], v249 offset:2048
	ds_read_b64_tr_b16 v[242:243], v249 offset:512
	ds_read_b64_tr_b16 v[244:245], v249 offset:2560
	ds_read_b64_tr_b16 v[128:129], v249 offset:4096
	ds_read_b64_tr_b16 v[130:131], v249 offset:6144
	ds_read_b64_tr_b16 v[132:133], v249 offset:4608
	ds_read_b64_tr_b16 v[134:135], v249 offset:6656
	v_add_f32_e32 v250, v140, v250
	v_add_f32_e32 v250, v141, v250
	v_add_f32_e32 v250, v142, v250
	v_add_f32_e32 v250, v143, v250
	v_cvt_pk_bf16_f32 v234, v136, v137
	v_cvt_pk_bf16_f32 v235, v138, v139
	v_cvt_pk_bf16_f32 v236, v140, v141
	v_cvt_pk_bf16_f32 v237, v142, v143
	v_add_f32_e32 v219, v219, v250
	ds_read_b64_tr_b16 v[136:137], v249 offset:1024
	ds_read_b64_tr_b16 v[138:139], v249 offset:3072
	ds_read_b64_tr_b16 v[140:141], v249 offset:1536
	ds_read_b64_tr_b16 v[142:143], v249 offset:3584
	s_waitcnt lgkmcnt(8)
	v_mfma_f32_32x32x16_bf16 v[112:127], v[230:233], v[238:241], v[112:127]
	v_mfma_f32_32x32x16_bf16 v[96:111], v[230:233], v[242:245], v[96:111]
	ds_read_b64_tr_b16 v[238:239], v249 offset:5120
	ds_read_b64_tr_b16 v[240:241], v249 offset:7168
	ds_read_b64_tr_b16 v[242:243], v249 offset:5632
	ds_read_b64_tr_b16 v[244:245], v249 offset:7680
	s_add_i32 s30, s85, s34
	s_add_i32 m0, s30, 0x8000
	s_nop 0
	global_load_lds_dwordx4 v222, s[2:3]
	s_waitcnt lgkmcnt(8)
	v_mfma_f32_32x32x16_bf16 v[112:127], v[234:237], v[128:131], v[112:127]
	v_mfma_f32_32x32x16_bf16 v[96:111], v[234:237], v[132:135], v[96:111]
	ds_read_b64_tr_b16 v[128:129], v249 offset:16384
	ds_read_b64_tr_b16 v[130:131], v249 offset:18432
	ds_read_b64_tr_b16 v[132:133], v249 offset:16896
	ds_read_b64_tr_b16 v[134:135], v249 offset:18944
	s_add_i32 s30, s85, s34
	s_add_i32 m0, s30, 0xa000
	s_nop 0
	global_load_lds_dwordx4 v221, s[2:3]
	s_waitcnt lgkmcnt(8)
	v_mfma_f32_32x32x16_bf16 v[80:95], v[230:233], v[136:139], v[80:95]
	v_mfma_f32_32x32x16_bf16 v[64:79], v[230:233], v[140:143], v[64:79]
	ds_read_b64_tr_b16 v[136:137], v249 offset:20480
	ds_read_b64_tr_b16 v[138:139], v249 offset:22528
	ds_read_b64_tr_b16 v[140:141], v249 offset:20992
	ds_read_b64_tr_b16 v[142:143], v249 offset:23040
	s_add_i32 s30, s85, s34
	s_add_i32 m0, s30, 0xc000
	s_nop 0
	global_load_lds_dwordx4 v246, s[2:3]
	s_waitcnt lgkmcnt(8)
	v_mfma_f32_32x32x16_bf16 v[80:95], v[234:237], v[238:241], v[80:95]
	v_mfma_f32_32x32x16_bf16 v[64:79], v[234:237], v[242:245], v[64:79]
	ds_read_b64_tr_b16 v[238:239], v249 offset:17408
	ds_read_b64_tr_b16 v[240:241], v249 offset:19456
	ds_read_b64_tr_b16 v[242:243], v249 offset:17920
	ds_read_b64_tr_b16 v[244:245], v249 offset:19968
	s_add_i32 s30, s85, s34
	s_add_i32 m0, s30, 0xe000
	s_nop 0
	global_load_lds_dwordx4 v247, s[2:3]
	s_waitcnt lgkmcnt(8)
	v_mfma_f32_32x32x16_bf16 v[32:47], v[230:233], v[128:131], v[32:47]
	v_mfma_f32_32x32x16_bf16 v[16:31], v[230:233], v[132:135], v[16:31]
	ds_read_b64_tr_b16 v[128:129], v249 offset:21504
	ds_read_b64_tr_b16 v[130:131], v249 offset:23552
	ds_read_b64_tr_b16 v[132:133], v249 offset:22016
	ds_read_b64_tr_b16 v[134:135], v249 offset:24064
	s_waitcnt lgkmcnt(8)
	v_mfma_f32_32x32x16_bf16 v[32:47], v[234:237], v[136:139], v[32:47]
	v_mfma_f32_32x32x16_bf16 v[16:31], v[234:237], v[140:143], v[16:31]
	s_waitcnt lgkmcnt(0)
	v_mfma_f32_32x32x16_bf16 v[48:63], v[230:233], v[238:241], v[48:63]
	s_waitcnt vmcnt(0)
	s_barrier
	s_add_u32 s86, s86, 0x4000
	s_addc_u32 s87, s87, 0
	s_add_u32 s2, s2, 0x8000
	s_addc_u32 s3, s3, 0
	v_mfma_f32_32x32x16_bf16 v[0:15], v[230:233], v[242:245], v[0:15]
	v_mfma_f32_32x32x16_bf16 v[48:63], v[234:237], v[128:131], v[48:63]
	v_mfma_f32_32x32x16_bf16 v[0:15], v[234:237], v[132:135], v[0:15]
	s_add_i32 s84, s84, 0x8000
	s_cmp_eq_u32 s84, 0x18000
	s_cselect_b32 s84, 0, s84
	s_add_i32 s40, s40, 1
	s_cmpk_eq_i32 s40, 0x82
	s_cbranch_scc0 .LBB0_1023
	s_barrier
	s_branch .Lattn_join_m1

; #define SBAR() __builtin_amdgcn_sched_barrier(0)
; #define PVR(S, DA, DB, vbase) do { S[0] = tr_read<v_rd_off(DA, 0, 0)>(vbase); S[1] = tr_read<v_rd_off(DA, 0, 1)>(vbase); S[2] = tr_read<v_rd_off(DB, 0, 0)>(vbase); S[3] = tr_read<v_rd_off(DB, 0, 1)>(vbase); \
;     S[4] = tr_read<v_rd_off(DA, 1, 0)>(vbase); S[5] = tr_read<v_rd_off(DA, 1, 1)>(vbase); S[6] = tr_read<v_rd_off(DB, 1, 0)>(vbase); S[7] = tr_read<v_rd_off(DB, 1, 1)>(vbase); } while (0)
; #define RAWBAR() do { asm volatile("s_waitcnt lgkmcnt(0)" ::: "memory"); __builtin_amdgcn_s_barrier(); asm volatile("" ::: "memory"); } while (0)
; #define RAWBAR() do { asm volatile("s_waitcnt lgkmcnt(0)" ::: "memory"); __builtin_amdgcn_s_barrier(); asm volatile("" ::: "memory"); } while (0)
; #define RAWBAR() do { asm volatile("s_waitcnt lgkmcnt(0)" ::: "memory"); __builtin_amdgcn_s_barrier(); asm volatile("" ::: "memory"); } while (0)
; #define RAWBAR() do { asm volatile("s_waitcnt lgkmcnt(0)" ::: "memory"); __builtin_amdgcn_s_barrier(); asm volatile("" ::: "memory"); } while (0)
; #define RAWBAR() do { asm volatile("s_waitcnt lgkmcnt(0)" ::: "memory"); __builtin_amdgcn_s_barrier(); asm volatile("" ::: "memory"); } while (0)
; template <int MODE> ...
;     ...
;   for (int j = 0; j < NT; ++j) {
;     const int buf = j & 1;
;     if (j + 1 < NT) { STAGE((j + 1) * KVBLK, buf ^ 1); }
;     const char* Kb = K_lds + buf * 16384;
;     f32x16 pe = {}, po = {};
; #pragma unroll
;     for (int d0 = 0; d0 < 8; d0 += 2) {
;       const bf16x8 k0 = *reinterpret_cast<const bf16x8*>(Kb + KSWZ(krow, (d0 * 16 + hi * 8) * 2));
;       const bf16x8 k1 = *reinterpret_cast<const bf16x8*>(Kb + KSWZ(krow, ((d0 + 1) * 16 + hi * 8) * 2));
;       pe = __builtin_amdgcn_mfma_f32_32x32x16_bf16(k0, qr[d0], pe, 0, 0, 0);
;       po = __builtin_amdgcn_mfma_f32_32x32x16_bf16(k1, qr[d0 + 1], po, 0, 0, 0); }
;     const int vo = vb0 + buf * 32768;
;     s16x4 R0_[8], R1_[8];
;     PVR(R0_, 0, 1, vo);
;     f32x16 p;
; #pragma unroll
;     for (int r = 0; r < 16; ++r) p[r] = __builtin_amdgcn_exp2f(fmaf(pe[r] + po[r], C, negMc));
;     float ps = 0.f;
; #pragma unroll
;     for (int r = 0; r < 16; ++r) ps += p[r];
;     lsum += ps;
;     const bf16x8 own0 = pk8(p, 0), own1 = pk8(p, 8);
;     SBAR();
;     PV_TAIL4(o, vo, vo + 16384, own0, own1);
;     asm volatile("s_waitcnt vmcnt(0)" ::: "memory");
;     RAWBAR();
.LattnB_m1:
	ds_read_b128 v[230:233], v229 offset:16384
	ds_read_b128 v[234:237], v228 offset:16384
	ds_read_b128 v[238:241], v227 offset:16384
	ds_read_b128 v[242:245], v226 offset:16384
	v_exp_f32_e32 v144, v144
	v_exp_f32_e32 v145, v145
	v_exp_f32_e32 v146, v146
	v_exp_f32_e32 v147, v147
	s_waitcnt lgkmcnt(2)
	v_mfma_f32_32x32x16_bf16 v[128:143], v[230:233], v[188:191], 0
	v_mfma_f32_32x32x16_bf16 v[128:143], v[234:237], v[184:187], v[128:143]
	ds_read_b128 v[230:233], v229 offset:16512
	ds_read_b128 v[234:237], v228 offset:16512
	v_exp_f32_e32 v148, v148
	v_exp_f32_e32 v149, v149
	v_exp_f32_e32 v150, v150
	v_exp_f32_e32 v151, v151
	v_add_f32_e32 v250, v144, v145
	v_add_f32_e32 v250, v146, v250
	v_add_f32_e32 v250, v147, v250
	s_waitcnt lgkmcnt(2)
	v_mfma_f32_32x32x16_bf16 v[128:143], v[238:241], v[180:183], v[128:143]
	v_mfma_f32_32x32x16_bf16 v[128:143], v[242:245], v[176:179], v[128:143]
	ds_read_b128 v[238:241], v227 offset:16512
	ds_read_b128 v[242:245], v226 offset:16512
	v_exp_f32_e32 v152, v152
	v_exp_f32_e32 v153, v153
	v_exp_f32_e32 v154, v154
	v_exp_f32_e32 v155, v155
	v_add_f32_e32 v250, v148, v250
	v_add_f32_e32 v250, v149, v250
	v_add_f32_e32 v250, v150, v250
	v_add_f32_e32 v250, v151, v250
	s_waitcnt lgkmcnt(2)
	v_mfma_f32_32x32x16_bf16 v[128:143], v[230:233], v[172:175], v[128:143]
	v_mfma_f32_32x32x16_bf16 v[128:143], v[234:237], v[168:171], v[128:143]
	v_exp_f32_e32 v156, v156
	v_exp_f32_e32 v157, v157
	v_exp_f32_e32 v158, v158
	v_exp_f32_e32 v159, v159
	v_add_f32_e32 v250, v152, v250
	v_add_f32_e32 v250, v153, v250
	v_add_f32_e32 v250, v154, v250
	v_add_f32_e32 v250, v155, v250
	v_cvt_pk_bf16_f32 v230, v144, v145
	v_cvt_pk_bf16_f32 v231, v146, v147
	v_cvt_pk_bf16_f32 v232, v148, v149
	v_cvt_pk_bf16_f32 v233, v150, v151
	s_waitcnt lgkmcnt(0)
	v_mfma_f32_32x32x16_bf16 v[128:143], v[238:241], v[164:167], v[128:143]
	v_mfma_f32_32x32x16_bf16 v[128:143], v[242:245], v[160:163], v[128:143]
	s_waitcnt vmcnt(0)
	s_barrier
	s_add_u32 s86, s86, 0x4000
	s_addc_u32 s87, s87, 0
	s_add_u32 s2, s2, 0x8000
	s_addc_u32 s3, s3, 0
	s_add_i32 m0, s34, 0x4000
	s_nop 0
	global_load_lds_dwordx4 v225, s[86:87]
	s_add_i32 m0, s34, 0x6000
	s_nop 0
	global_load_lds_dwordx4 v223, s[86:87]
	v_add_u32_e32 v249, s84, v218
	s_sub_u32 s85, s84, 0x8000
	s_cmp_eq_u32 s84, 0
	s_cselect_b32 s85, 0x10000, s85
	ds_read_b64_tr_b16 v[238:239], v249 offset:0
	ds_read_b64_tr_b16 v[240:241], v249 offset:2048
	ds_read_b64_tr_b16 v[242:243], v249 offset:512
	ds_read_b64_tr_b16 v[244:245], v249 offset:2560
	ds_read_b64_tr_b16 v[144:145], v249 offset:4096
	ds_read_b64_tr_b16 v[146:147], v249 offset:6144
	ds_read_b64_tr_b16 v[148:149], v249 offset:4608
	ds_read_b64_tr_b16 v[150:151], v249 offset:6656
	v_add_f32_e32 v250, v156, v250
	v_add_f32_e32 v250, v157, v250
	v_add_f32_e32 v250, v158, v250
	v_add_f32_e32 v250, v159, v250
	v_cvt_pk_bf16_f32 v234, v152, v153
	v_cvt_pk_bf16_f32 v235, v154, v155
	v_cvt_pk_bf16_f32 v236, v156, v157
	v_cvt_pk_bf16_f32 v237, v158, v159
	v_add_f32_e32 v219, v219, v250
	ds_read_b64_tr_b16 v[152:153], v249 offset:1024
	ds_read_b64_tr_b16 v[154:155], v249 offset:3072
	ds_read_b64_tr_b16 v[156:157], v249 offset:1536
	ds_read_b64_tr_b16 v[158:159], v249 offset:3584
	s_waitcnt lgkmcnt(8)
	v_mfma_f32_32x32x16_bf16 v[112:127], v[230:233], v[238:241], v[112:127]
	v_mfma_f32_32x32x16_bf16 v[96:111], v[230:233], v[242:245], v[96:111]
	ds_read_b64_tr_b16 v[238:239], v249 offset:5120
	ds_read_b64_tr_b16 v[240:241], v249 offset:7168
	ds_read_b64_tr_b16 v[242:243], v249 offset:5632
	ds_read_b64_tr_b16 v[244:245], v249 offset:7680
	s_add_i32 s30, s85, s34
	s_add_i32 m0, s30, 0x8000
	s_nop 0
	global_load_lds_dwordx4 v222, s[2:3]
	s_waitcnt lgkmcnt(8)
	v_mfma_f32_32x32x16_bf16 v[112:127], v[234:237], v[144:147], v[112:127]
	v_mfma_f32_32x32x16_bf16 v[96:111], v[234:237], v[148:151], v[96:111]
	ds_read_b64_tr_b16 v[144:145], v249 offset:16384
	ds_read_b64_tr_b16 v[146:147], v249 offset:18432
	ds_read_b64_tr_b16 v[148:149], v249 offset:16896
	ds_read_b64_tr_b16 v[150:151], v249 offset:18944
	s_add_i32 s30, s85, s34
	s_add_i32 m0, s30, 0xa000
	s_nop 0
	global_load_lds_dwordx4 v221, s[2:3]
	s_waitcnt lgkmcnt(8)
	v_mfma_f32_32x32x16_bf16 v[80:95], v[230:233], v[152:155], v[80:95]
	v_mfma_f32_32x32x16_bf16 v[64:79], v[230:233], v[156:159], v[64:79]
	ds_read_b64_tr_b16 v[152:153], v249 offset:20480
	ds_read_b64_tr_b16 v[154:155], v249 offset:22528
	ds_read_b64_tr_b16 v[156:157], v249 offset:20992
	ds_read_b64_tr_b16 v[158:159], v249 offset:23040
	s_add_i32 s30, s85, s34
	s_add_i32 m0, s30, 0xc000
	s_nop 0
	global_load_lds_dwordx4 v246, s[2:3]
	s_waitcnt lgkmcnt(8)
	v_mfma_f32_32x32x16_bf16 v[80:95], v[234:237], v[238:241], v[80:95]
	v_mfma_f32_32x32x16_bf16 v[64:79], v[234:237], v[242:245], v[64:79]
	ds_read_b64_tr_b16 v[238:239], v249 offset:17408
	ds_read_b64_tr_b16 v[240:241], v249 offset:19456
	ds_read_b64_tr_b16 v[242:243], v249 offset:17920
	ds_read_b64_tr_b16 v[244:245], v249 offset:19968
	s_add_i32 s30, s85, s34
	s_add_i32 m0, s30, 0xe000
	s_nop 0
	global_load_lds_dwordx4 v247, s[2:3]
	s_waitcnt lgkmcnt(8)
	v_mfma_f32_32x32x16_bf16 v[32:47], v[230:233], v[144:147], v[32:47]
	v_mfma_f32_32x32x16_bf16 v[16:31], v[230:233], v[148:151], v[16:31]
	ds_read_b64_tr_b16 v[144:145], v249 offset:21504
	ds_read_b64_tr_b16 v[146:147], v249 offset:23552
	ds_read_b64_tr_b16 v[148:149], v249 offset:22016
	ds_read_b64_tr_b16 v[150:151], v249 offset:24064
	s_waitcnt lgkmcnt(8)
	v_mfma_f32_32x32x16_bf16 v[32:47], v[234:237], v[152:155], v[32:47]
	v_mfma_f32_32x32x16_bf16 v[16:31], v[234:237], v[156:159], v[16:31]
	s_waitcnt lgkmcnt(0)
; #define SBAR() __builtin_amdgcn_sched_barrier(0)
; #define PVR(S, DA, DB, vbase) do { S[0] = tr_read<v_rd_off(DA, 0, 0)>(vbase); S[1] = tr_read<v_rd_off(DA, 0, 1)>(vbase); S[2] = tr_read<v_rd_off(DB, 0, 0)>(vbase); S[3] = tr_read<v_rd_off(DB, 0, 1)>(vbase); \
;     S[4] = tr_read<v_rd_off(DA, 1, 0)>(vbase); S[5] = tr_read<v_rd_off(DA, 1, 1)>(vbase); S[6] = tr_read<v_rd_off(DB, 1, 0)>(vbase); S[7] = tr_read<v_rd_off(DB, 1, 1)>(vbase); } while (0)
; #define RAWBAR() do { asm volatile("s_waitcnt lgkmcnt(0)" ::: "memory"); __builtin_amdgcn_s_barrier(); asm volatile("" ::: "memory"); } while (0)
; #define RAWBAR() do { asm volatile("s_waitcnt lgkmcnt(0)" ::: "memory"); __builtin_amdgcn_s_barrier(); asm volatile("" ::: "memory"); } while (0)
; #define RAWBAR() do { asm volatile("s_waitcnt lgkmcnt(0)" ::: "memory"); __builtin_amdgcn_s_barrier(); asm volatile("" ::: "memory"); } while (0)
; #define RAWBAR() do { asm volatile("s_waitcnt lgkmcnt(0)" ::: "memory"); __builtin_amdgcn_s_barrier(); asm volatile("" ::: "memory"); } while (0)
; #define RAWBAR() do { asm volatile("s_waitcnt lgkmcnt(0)" ::: "memory"); __builtin_amdgcn_s_barrier(); asm volatile("" ::: "memory"); } while (0)
; template <int MODE> ...
;     ...
;   for (int j = 0; j < NT; ++j) {
;     const int buf = j & 1;
;     if (j + 1 < NT) { STAGE((j + 1) * KVBLK, buf ^ 1); }
;     const char* Kb = K_lds + buf * 16384;
;     f32x16 pe = {}, po = {};
; #pragma unroll
;     for (int d0 = 0; d0 < 8; d0 += 2) {
;       const bf16x8 k0 = *reinterpret_cast<const bf16x8*>(Kb + KSWZ(krow, (d0 * 16 + hi * 8) * 2));
;       const bf16x8 k1 = *reinterpret_cast<const bf16x8*>(Kb + KSWZ(krow, ((d0 + 1) * 16 + hi * 8) * 2));
;       pe = __builtin_amdgcn_mfma_f32_32x32x16_bf16(k0, qr[d0], pe, 0, 0, 0);
;       po = __builtin_amdgcn_mfma_f32_32x32x16_bf16(k1, qr[d0 + 1], po, 0, 0, 0); }
;     const int vo = vb0 + buf * 32768;
;     s16x4 R0_[8], R1_[8];
;     PVR(R0_, 0, 1, vo);
;     f32x16 p;
; #pragma unroll
;     for (int r = 0; r < 16; ++r) p[r] = __builtin_amdgcn_exp2f(fmaf(pe[r] + po[r], C, negMc));
;     float ps = 0.f;
; #pragma unroll
;     for (int r = 0; r < 16; ++r) ps += p[r];
;     lsum += ps;
;     const bf16x8 own0 = pk8(p, 0), own1 = pk8(p, 8);
;     SBAR();
;     PV_TAIL4(o, vo, vo + 16384, own0, own1);
;     asm volatile("s_waitcnt vmcnt(0)" ::: "memory");
;     RAWBAR();
	v_mfma_f32_32x32x16_bf16 v[48:63], v[230:233], v[238:241], v[48:63]
	v_mfma_f32_32x32x16_bf16 v[0:15], v[230:233], v[242:245], v[0:15]
	v_mfma_f32_32x32x16_bf16 v[48:63], v[234:237], v[144:147], v[48:63]
	v_mfma_f32_32x32x16_bf16 v[0:15], v[234:237], v[148:151], v[0:15]
	s_add_i32 s84, s84, 0x8000
	s_cmp_eq_u32 s84, 0x18000
	s_cselect_b32 s84, 0, s84
	ds_read_b128 v[230:233], v229 offset:0
	ds_read_b128 v[234:237], v228 offset:0
	ds_read_b128 v[238:241], v227 offset:0
	ds_read_b128 v[242:245], v226 offset:0
	v_exp_f32_e32 v128, v128
	v_exp_f32_e32 v129, v129
	v_exp_f32_e32 v130, v130
	v_exp_f32_e32 v131, v131
	s_waitcnt lgkmcnt(2)
	v_mfma_f32_32x32x16_bf16 v[144:159], v[230:233], v[188:191], 0
	v_mfma_f32_32x32x16_bf16 v[144:159], v[234:237], v[184:187], v[144:159]
	ds_read_b128 v[230:233], v229 offset:128
	ds_read_b128 v[234:237], v228 offset:128
	v_exp_f32_e32 v132, v132
	v_exp_f32_e32 v133, v133
	v_exp_f32_e32 v134, v134
	v_exp_f32_e32 v135, v135
	v_add_f32_e32 v250, v128, v129
	v_add_f32_e32 v250, v130, v250
	v_add_f32_e32 v250, v131, v250
	s_waitcnt lgkmcnt(2)
	v_mfma_f32_32x32x16_bf16 v[144:159], v[238:241], v[180:183], v[144:159]
	v_mfma_f32_32x32x16_bf16 v[144:159], v[242:245], v[176:179], v[144:159]
	ds_read_b128 v[238:241], v227 offset:128
	ds_read_b128 v[242:245], v226 offset:128
	v_exp_f32_e32 v136, v136
	v_exp_f32_e32 v137, v137
	v_exp_f32_e32 v138, v138
	v_exp_f32_e32 v139, v139
	v_add_f32_e32 v250, v132, v250
	v_add_f32_e32 v250, v133, v250
	v_add_f32_e32 v250, v134, v250
	v_add_f32_e32 v250, v135, v250
	s_waitcnt lgkmcnt(2)
	v_mfma_f32_32x32x16_bf16 v[144:159], v[230:233], v[172:175], v[144:159]
	v_mfma_f32_32x32x16_bf16 v[144:159], v[234:237], v[168:171], v[144:159]
	v_exp_f32_e32 v140, v140
	v_exp_f32_e32 v141, v141
	v_exp_f32_e32 v142, v142
	v_exp_f32_e32 v143, v143
	v_add_f32_e32 v250, v136, v250
	v_add_f32_e32 v250, v137, v250
	v_add_f32_e32 v250, v138, v250
	v_add_f32_e32 v250, v139, v250
	v_cvt_pk_bf16_f32 v230, v128, v129
	v_cvt_pk_bf16_f32 v231, v130, v131
	v_cvt_pk_bf16_f32 v232, v132, v133
	v_cvt_pk_bf16_f32 v233, v134, v135
	s_waitcnt lgkmcnt(0)
	v_mfma_f32_32x32x16_bf16 v[144:159], v[238:241], v[164:167], v[144:159]
	v_mfma_f32_32x32x16_bf16 v[144:159], v[242:245], v[160:163], v[144:159]
	s_waitcnt vmcnt(0)
	s_barrier
	s_add_u32 s86, s86, 0x4000
	s_addc_u32 s87, s87, 0
	s_add_u32 s2, s2, 0x8000
	s_addc_u32 s3, s3, 0
	s_mov_b32 m0, s34
	s_nop 0
	global_load_lds_dwordx4 v225, s[86:87]
	s_add_i32 m0, s34, 0x2000
	s_nop 0
	global_load_lds_dwordx4 v223, s[86:87]
	v_add_u32_e32 v249, s84, v218
	s_sub_u32 s85, s84, 0x8000
	s_cmp_eq_u32 s84, 0
	s_cselect_b32 s85, 0x10000, s85
	ds_read_b64_tr_b16 v[238:239], v249 offset:0
	ds_read_b64_tr_b16 v[240:241], v249 offset:2048
	ds_read_b64_tr_b16 v[242:243], v249 offset:512
	ds_read_b64_tr_b16 v[244:245], v249 offset:2560
	ds_read_b64_tr_b16 v[128:129], v249 offset:4096
	ds_read_b64_tr_b16 v[130:131], v249 offset:6144
	ds_read_b64_tr_b16 v[132:133], v249 offset:4608
	ds_read_b64_tr_b16 v[134:135], v249 offset:6656
	v_add_f32_e32 v250, v140, v250
	v_add_f32_e32 v250, v141, v250
	v_add_f32_e32 v250, v142, v250
	v_add_f32_e32 v250, v143, v250
	v_cvt_pk_bf16_f32 v234, v136, v137
	v_cvt_pk_bf16_f32 v235, v138, v139
	v_cvt_pk_bf16_f32 v236, v140, v141
	v_cvt_pk_bf16_f32 v237, v142, v143
	v_add_f32_e32 v219, v219, v250
	ds_read_b64_tr_b16 v[136:137], v249 offset:1024
	ds_read_b64_tr_b16 v[138:139], v249 offset:3072
	ds_read_b64_tr_b16 v[140:141], v249 offset:1536
	ds_read_b64_tr_b16 v[142:143], v249 offset:3584
	s_waitcnt lgkmcnt(8)
	v_mfma_f32_32x32x16_bf16 v[112:127], v[230:233], v[238:241], v[112:127]
	v_mfma_f32_32x32x16_bf16 v[96:111], v[230:233], v[242:245], v[96:111]
	ds_read_b64_tr_b16 v[238:239], v249 offset:5120
	ds_read_b64_tr_b16 v[240:241], v249 offset:7168
	ds_read_b64_tr_b16 v[242:243], v249 offset:5632
	ds_read_b64_tr_b16 v[244:245], v249 offset:7680
	s_add_i32 s30, s85, s34
	s_add_i32 m0, s30, 0x8000
	s_nop 0
	global_load_lds_dwordx4 v222, s[2:3]
	s_waitcnt lgkmcnt(8)
	v_mfma_f32_32x32x16_bf16 v[112:127], v[234:237], v[128:131], v[112:127]
	v_mfma_f32_32x32x16_bf16 v[96:111], v[234:237], v[132:135], v[96:111]
	ds_read_b64_tr_b16 v[128:129], v249 offset:16384
	ds_read_b64_tr_b16 v[130:131], v249 offset:18432
	ds_read_b64_tr_b16 v[132:133], v249 offset:16896
	ds_read_b64_tr_b16 v[134:135], v249 offset:18944
	s_add_i32 s30, s85, s34
	s_add_i32 m0, s30, 0xa000
	s_nop 0
	global_load_lds_dwordx4 v221, s[2:3]
	s_waitcnt lgkmcnt(8)
	v_mfma_f32_32x32x16_bf16 v[80:95], v[230:233], v[136:139], v[80:95]
	v_mfma_f32_32x32x16_bf16 v[64:79], v[230:233], v[140:143], v[64:79]
	ds_read_b64_tr_b16 v[136:137], v249 offset:20480
	ds_read_b64_tr_b16 v[138:139], v249 offset:22528
	ds_read_b64_tr_b16 v[140:141], v249 offset:20992
	ds_read_b64_tr_b16 v[142:143], v249 offset:23040
	s_add_i32 s30, s85, s34
	s_add_i32 m0, s30, 0xc000
	s_nop 0
	global_load_lds_dwordx4 v246, s[2:3]
	s_waitcnt lgkmcnt(8)
	v_mfma_f32_32x32x16_bf16 v[80:95], v[234:237], v[238:241], v[80:95]
	v_mfma_f32_32x32x16_bf16 v[64:79], v[234:237], v[242:245], v[64:79]
	ds_read_b64_tr_b16 v[238:239], v249 offset:17408
	ds_read_b64_tr_b16 v[240:241], v249 offset:19456
	ds_read_b64_tr_b16 v[242:243], v249 offset:17920
	ds_read_b64_tr_b16 v[244:245], v249 offset:19968
	s_add_i32 s30, s85, s34
	s_add_i32 m0, s30, 0xe000
	s_nop 0
	global_load_lds_dwordx4 v247, s[2:3]
	s_waitcnt lgkmcnt(8)
	v_mfma_f32_32x32x16_bf16 v[32:47], v[230:233], v[128:131], v[32:47]
	v_mfma_f32_32x32x16_bf16 v[16:31], v[230:233], v[132:135], v[16:31]
	ds_read_b64_tr_b16 v[128:129], v249 offset:21504
	ds_read_b64_tr_b16 v[130:131], v249 offset:23552
	ds_read_b64_tr_b16 v[132:133], v249 offset:22016
	ds_read_b64_tr_b16 v[134:135], v249 offset:24064
	s_waitcnt lgkmcnt(8)
	v_mfma_f32_32x32x16_bf16 v[32:47], v[234:237], v[136:139], v[32:47]
	v_mfma_f32_32x32x16_bf16 v[16:31], v[234:237], v[140:143], v[16:31]
	s_waitcnt lgkmcnt(0)
	v_mfma_f32_32x32x16_bf16 v[48:63], v[230:233], v[238:241], v[48:63]
	v_mfma_f32_32x32x16_bf16 v[0:15], v[230:233], v[242:245], v[0:15]
	v_mfma_f32_32x32x16_bf16 v[48:63], v[234:237], v[128:131], v[48:63]
	v_mfma_f32_32x32x16_bf16 v[0:15], v[234:237], v[132:135], v[0:15]
	s_add_i32 s84, s84, 0x8000
	s_cmp_eq_u32 s84, 0x18000
	s_cselect_b32 s84, 0, s84
	s_add_i32 s40, s40, 1
	s_cmpk_eq_i32 s40, 0x82
	s_cbranch_scc0 .LattnB_m1
	s_waitcnt vmcnt(0)
	s_barrier
